# K-loop MFMA-wave priority raised from 1 to 3 (set before the barrier, cleared after the closing barrier); on top of trimmed block
# speedup vs baseline: 1.0011x; 1.0011x over previous
; #define PG8_STAGE(bufoff, gbase, voff) do { _Pragma("unroll") for (int _i = 0; _i < 2; ++_i) \
;         __builtin_amdgcn_global_load_lds((const unsigned*)((const char*)(gbase) + (voff)[_i]), (PG8_LAS unsigned*)(lds + (bufoff) + ldsw + _i * 8192), 16, 0, 0); } while (0)
; #define PG8_LDA(dst, b, h) do { _Pragma("unroll") for (int m = 0; m < 4; ++m) _Pragma("unroll") for (int k = 0; k < 2; ++k) dst[m][k] = *(const PG8_LAS bf16x8*)(lds + PG8_SA(b, h) + aoff + m * 2048 + k * 1024); } while (0)
; #define PG8_LDB(dst, b, h) do { _Pragma("unroll") for (int n = 0; n < 2; ++n) _Pragma("unroll") for (int k = 0; k < 2; ++k) dst[n][k] = *(const PG8_LAS bf16x8*)(lds + PG8_SB(b, h) + boff + n * 2048 + k * 1024); } while (0)
; #define PG8_MMA(ai, bj, At, Bt) do { __builtin_amdgcn_s_setprio(1); _Pragma("unroll") for (int m = 0; m < 4; ++m) _Pragma("unroll") for (int n = 0; n < 2; ++n) _Pragma("unroll") for (int k = 0; k < 2; ++k) \
;         acc[ai][bj][m][n] = __builtin_amdgcn_mfma_f32_16x16x32_bf16(Bt[n][k], At[m][k], acc[ai][bj][m][n], 0, 0, 0); __builtin_amdgcn_s_setprio(0); } while (0)
; #define PG8_WAIT_V(n) asm volatile("s_waitcnt vmcnt(" #n ")" ::: "memory")
; #define PG8_BAR __builtin_amdgcn_s_barrier()
; template <class Epi, class Sched, bool ALIGN_EPI = false, bool SP2 = false>
; __device__ __forceinline__ void gemm_phase(PG8_LAS unsigned char* lds, const Gemm g, const Sched& S, const Epi& E) {
;     ...
;         for (int t = 0; t < nt; t += 2) {
;             const bool last = (t == nt - 2);
;             const char* a1 = cA + (size_t)(t + 1) * kstep;
;             const char* a2 = last ? nA : cA + (size_t)(t + 2) * kstep; const char* b2 = last ? nB : cB + (size_t)(t + 2) * kstep;
;             const char* a3 = a2 + kstep; const char* b3 = b2 + kstep;
;             if (last && has_next) S.a_ready(nxt);
;             if constexpr (SP2) {
;             PG8_LDB(B0, 0, 0); PG8_LDB(B1, 0, 1); PG8_SCHED; PG8_LDA(At, 0, 0); PG8_STAGE(PG8_SA(1, 1), a1 + hstep, voffA);
;             PG8_WAIT_V(8); PG8_WAIT_L(0); PG8_BAR; PG8_MMA(0, 0, At, B0); PG8_MMA(0, 1, At, B1); PG8_BAR; PG8_SCHED;
;             PG8_LDA(At, 0, 1); PG8_STAGE(PG8_SB(0, 0), b2, voffB); PG8_STAGE(PG8_SB(0, 1), b2 + hstep, voffB); PG8_STAGE(PG8_SA(0, 0), a2, voffA);
;             PG8_WAIT_V(8); PG8_WAIT_L(0); PG8_BAR; PG8_MMA(1, 0, At, B0); PG8_MMA(1, 1, At, B1); PG8_BAR; PG8_SCHED;
.LBB0_124:
	s_add_u32 s26, s62, 0xfff00080
	s_addc_u32 s27, s63, -1
	s_add_i32 s65, 0, 0x10000
	s_cmp_eq_u32 s17, 60
	s_cselect_b32 s29, s30, s27
	s_cselect_b32 s28, s31, s26
	v_add_u32_e32 v170, s65, v182
	s_cselect_b32 s27, s53, s16
	s_cselect_b32 s26, s55, vcc_lo
	s_add_i32 s70, 0, 0x14000
	ds_read_b128 v[122:125], v170
	ds_read_b128 v[126:129], v170 offset:1024
	ds_read_b128 v[130:133], v170 offset:2048
	ds_read_b128 v[172:175], v170 offset:3072
	v_add_u32_e32 v170, s70, v182
	ds_read_b128 v[176:179], v170
	ds_read_b128 v[192:195], v170 offset:1024
	ds_read_b128 v[196:199], v170 offset:2048
	ds_read_b128 v[200:203], v170 offset:3072
	v_lshl_add_u64 v[180:181], s[62:63], 0, v[156:157]
	s_add_i32 m0, s10, 0xc000
	ds_read_b128 v[204:207], v191
	ds_read_b128 v[220:223], v191 offset:1024
	ds_read_b128 v[224:227], v191 offset:2048
	ds_read_b128 v[228:231], v191 offset:3072
	ds_read_b128 v[232:235], v191 offset:4096
	ds_read_b128 v[236:239], v191 offset:5120
	ds_read_b128 v[240:243], v191 offset:6144
	ds_read_b128 v[244:247], v191 offset:7168
	global_load_lds_dwordx4 v[180:181], off
	v_lshl_add_u64 v[180:181], s[62:63], 0, v[154:155]
	s_add_i32 m0, s10, 0xe000
	s_nop 0
	global_load_lds_dwordx4 v[180:181], off
	s_waitcnt vmcnt(8)
	s_waitcnt lgkmcnt(0)
	s_setprio 3
	s_barrier
	v_mfma_f32_16x16x32_bf16 v[118:121], v[122:125], v[204:207], v[118:121]
	v_mfma_f32_16x16x32_bf16 v[138:141], v[130:133], v[204:207], v[138:141]
	v_mfma_f32_16x16x32_bf16 v[102:105], v[122:125], v[224:227], v[102:105]
	v_mfma_f32_16x16x32_bf16 v[114:117], v[130:133], v[224:227], v[114:117]
	v_mfma_f32_16x16x32_bf16 v[86:89], v[122:125], v[232:235], v[86:89]
	v_mfma_f32_16x16x32_bf16 v[98:101], v[130:133], v[232:235], v[98:101]
	v_mfma_f32_16x16x32_bf16 v[70:73], v[122:125], v[240:243], v[70:73]
	v_mfma_f32_16x16x32_bf16 v[82:85], v[130:133], v[240:243], v[82:85]
	v_mfma_f32_16x16x32_bf16 v[118:121], v[126:129], v[220:223], v[118:121]
	v_mfma_f32_16x16x32_bf16 v[138:141], v[172:175], v[220:223], v[138:141]
	v_mfma_f32_16x16x32_bf16 v[102:105], v[126:129], v[228:231], v[102:105]
	v_mfma_f32_16x16x32_bf16 v[114:117], v[172:175], v[228:231], v[114:117]
	v_mfma_f32_16x16x32_bf16 v[86:89], v[126:129], v[236:239], v[86:89]
	v_mfma_f32_16x16x32_bf16 v[98:101], v[172:175], v[236:239], v[98:101]
	v_mfma_f32_16x16x32_bf16 v[70:73], v[126:129], v[244:247], v[70:73]
	v_mfma_f32_16x16x32_bf16 v[82:85], v[172:175], v[244:247], v[82:85]
	v_mfma_f32_16x16x32_bf16 v[134:137], v[176:179], v[204:207], v[134:137]
	v_mfma_f32_16x16x32_bf16 v[110:113], v[196:199], v[204:207], v[110:113]
	v_mfma_f32_16x16x32_bf16 v[106:109], v[176:179], v[224:227], v[106:109]
	v_mfma_f32_16x16x32_bf16 v[94:97], v[196:199], v[224:227], v[94:97]
	v_mfma_f32_16x16x32_bf16 v[90:93], v[176:179], v[232:235], v[90:93]
	v_mfma_f32_16x16x32_bf16 v[78:81], v[196:199], v[232:235], v[78:81]
	v_mfma_f32_16x16x32_bf16 v[74:77], v[176:179], v[240:243], v[74:77]
	v_mfma_f32_16x16x32_bf16 v[66:69], v[196:199], v[240:243], v[66:69]
	v_mfma_f32_16x16x32_bf16 v[134:137], v[192:195], v[220:223], v[134:137]
	v_mfma_f32_16x16x32_bf16 v[110:113], v[200:203], v[220:223], v[110:113]
	v_mfma_f32_16x16x32_bf16 v[106:109], v[192:195], v[228:231], v[106:109]
	v_mfma_f32_16x16x32_bf16 v[94:97], v[200:203], v[228:231], v[94:97]
	v_mfma_f32_16x16x32_bf16 v[90:93], v[192:195], v[236:239], v[90:93]
	v_mfma_f32_16x16x32_bf16 v[78:81], v[200:203], v[236:239], v[78:81]
	v_mfma_f32_16x16x32_bf16 v[74:77], v[192:195], v[244:247], v[74:77]
	v_mfma_f32_16x16x32_bf16 v[66:69], v[200:203], v[244:247], v[66:69]
	s_barrier
	s_setprio 0
	s_add_i32 s65, s65, s9
	v_lshl_add_u64 v[180:181], s[26:27], 0, v[158:159]
	s_mov_b32 m0, s65
	ds_read_b128 v[204:207], v191 offset:16384
	ds_read_b128 v[220:223], v191 offset:17408
	ds_read_b128 v[224:227], v191 offset:18432
	ds_read_b128 v[228:231], v191 offset:19456
	ds_read_b128 v[232:235], v191 offset:20480
	ds_read_b128 v[236:239], v191 offset:21504
	ds_read_b128 v[240:243], v191 offset:22528
	ds_read_b128 v[244:247], v191 offset:23552
	global_load_lds_dwordx4 v[180:181], off
	s_add_i32 m0, s65, 0x2000
	s_add_u32 s68, s26, 0x100000
	v_lshl_add_u64 v[208:209], s[26:27], 0, v[142:143]
	s_addc_u32 s69, s27, 0
	s_add_i32 s65, s70, s9
	global_load_lds_dwordx4 v[208:209], off
	v_lshl_add_u64 v[248:249], s[68:69], 0, v[158:159]
	s_mov_b32 m0, s65
	v_lshl_add_u64 v[170:171], s[28:29], 0, v[144:145]
	global_load_lds_dwordx4 v[248:249], off
	v_lshl_add_u64 v[248:249], s[68:69], 0, v[142:143]
	s_add_i32 m0, s65, 0x2000
	s_nop 0
	global_load_lds_dwordx4 v[248:249], off
	v_lshl_add_u64 v[248:249], s[28:29], 0, v[146:147]
	s_mov_b32 m0, s10
	s_nop 0
	global_load_lds_dwordx4 v[248:249], off
	s_mov_b32 m0, s11
	s_nop 0
	global_load_lds_dwordx4 v[170:171], off
	s_waitcnt vmcnt(8)
	s_waitcnt lgkmcnt(0)
	s_setprio 3
	s_barrier
; #define PG8_STAGE(bufoff, gbase, voff) do { _Pragma("unroll") for (int _i = 0; _i < 2; ++_i) \
;         __builtin_amdgcn_global_load_lds((const unsigned*)((const char*)(gbase) + (voff)[_i]), (PG8_LAS unsigned*)(lds + (bufoff) + ldsw + _i * 8192), 16, 0, 0); } while (0)
; #define PG8_LDA(dst, b, h) do { _Pragma("unroll") for (int m = 0; m < 4; ++m) _Pragma("unroll") for (int k = 0; k < 2; ++k) dst[m][k] = *(const PG8_LAS bf16x8*)(lds + PG8_SA(b, h) + aoff + m * 2048 + k * 1024); } while (0)
; #define PG8_LDB(dst, b, h) do { _Pragma("unroll") for (int n = 0; n < 2; ++n) _Pragma("unroll") for (int k = 0; k < 2; ++k) dst[n][k] = *(const PG8_LAS bf16x8*)(lds + PG8_SB(b, h) + boff + n * 2048 + k * 1024); } while (0)
; #define PG8_MMA(ai, bj, At, Bt) do { __builtin_amdgcn_s_setprio(1); _Pragma("unroll") for (int m = 0; m < 4; ++m) _Pragma("unroll") for (int n = 0; n < 2; ++n) _Pragma("unroll") for (int k = 0; k < 2; ++k) \
;         acc[ai][bj][m][n] = __builtin_amdgcn_mfma_f32_16x16x32_bf16(Bt[n][k], At[m][k], acc[ai][bj][m][n], 0, 0, 0); __builtin_amdgcn_s_setprio(0); } while (0)
; #define PG8_WAIT_V(n) asm volatile("s_waitcnt vmcnt(" #n ")" ::: "memory")
; #define PG8_WAIT_L(n) asm volatile("s_waitcnt lgkmcnt(" #n ")" ::: "memory")
; #define PG8_BAR __builtin_amdgcn_s_barrier()
; #define PG8_SCHED __builtin_amdgcn_sched_barrier(0)
; template <class Epi, class Sched, bool ALIGN_EPI = false, bool SP2 = false>
; __device__ __forceinline__ void gemm_phase(PG8_LAS unsigned char* lds, const Gemm g, const Sched& S, const Epi& E) {
;     ...
;             PG8_WAIT_V(8); PG8_WAIT_L(0); PG8_BAR; PG8_MMA(1, 0, At, B0); PG8_MMA(1, 1, At, B1); PG8_BAR; PG8_SCHED;
;             PG8_LDB(B0, 1, 0); PG8_LDB(B1, 1, 1); PG8_SCHED; PG8_LDA(At, 1, 0); PG8_STAGE(PG8_SA(0, 1), a2 + hstep, voffA);
;             PG8_WAIT_V(8); PG8_WAIT_L(0); PG8_BAR; PG8_MMA(0, 0, At, B0); PG8_MMA(0, 1, At, B1); PG8_BAR; PG8_SCHED;
	v_mfma_f32_16x16x32_bf16 v[54:57], v[122:125], v[204:207], v[54:57]
	v_mfma_f32_16x16x32_bf16 v[62:65], v[130:133], v[204:207], v[62:65]
	v_mfma_f32_16x16x32_bf16 v[38:41], v[122:125], v[224:227], v[38:41]
	v_mfma_f32_16x16x32_bf16 v[50:53], v[130:133], v[224:227], v[50:53]
	v_mfma_f32_16x16x32_bf16 v[22:25], v[122:125], v[232:235], v[22:25]
	v_mfma_f32_16x16x32_bf16 v[34:37], v[130:133], v[232:235], v[34:37]
	v_mfma_f32_16x16x32_bf16 v[6:9], v[122:125], v[240:243], v[6:9]
	v_mfma_f32_16x16x32_bf16 v[18:21], v[130:133], v[240:243], v[18:21]
	v_mfma_f32_16x16x32_bf16 v[54:57], v[126:129], v[220:223], v[54:57]
	v_mfma_f32_16x16x32_bf16 v[62:65], v[172:175], v[220:223], v[62:65]
	v_mfma_f32_16x16x32_bf16 v[38:41], v[126:129], v[228:231], v[38:41]
	v_mfma_f32_16x16x32_bf16 v[50:53], v[172:175], v[228:231], v[50:53]
	v_mfma_f32_16x16x32_bf16 v[22:25], v[126:129], v[236:239], v[22:25]
	v_mfma_f32_16x16x32_bf16 v[34:37], v[172:175], v[236:239], v[34:37]
	v_mfma_f32_16x16x32_bf16 v[6:9], v[126:129], v[244:247], v[6:9]
	v_mfma_f32_16x16x32_bf16 v[18:21], v[172:175], v[244:247], v[18:21]
	v_mfma_f32_16x16x32_bf16 v[58:61], v[176:179], v[204:207], v[58:61]
	v_mfma_f32_16x16x32_bf16 v[46:49], v[196:199], v[204:207], v[46:49]
	v_mfma_f32_16x16x32_bf16 v[42:45], v[176:179], v[224:227], v[42:45]
	v_mfma_f32_16x16x32_bf16 v[30:33], v[196:199], v[224:227], v[30:33]
	v_mfma_f32_16x16x32_bf16 v[26:29], v[176:179], v[232:235], v[26:29]
	v_mfma_f32_16x16x32_bf16 v[14:17], v[196:199], v[232:235], v[14:17]
	v_mfma_f32_16x16x32_bf16 v[10:13], v[176:179], v[240:243], v[10:13]
	v_mfma_f32_16x16x32_bf16 v[2:5], v[196:199], v[240:243], v[2:5]
	v_mfma_f32_16x16x32_bf16 v[58:61], v[192:195], v[220:223], v[58:61]
	v_mfma_f32_16x16x32_bf16 v[46:49], v[200:203], v[220:223], v[46:49]
	v_mfma_f32_16x16x32_bf16 v[42:45], v[192:195], v[228:231], v[42:45]
	v_mfma_f32_16x16x32_bf16 v[30:33], v[200:203], v[228:231], v[30:33]
	v_mfma_f32_16x16x32_bf16 v[26:29], v[192:195], v[236:239], v[26:29]
	v_mfma_f32_16x16x32_bf16 v[14:17], v[200:203], v[236:239], v[14:17]
	v_mfma_f32_16x16x32_bf16 v[10:13], v[192:195], v[244:247], v[10:13]
	v_mfma_f32_16x16x32_bf16 v[2:5], v[200:203], v[244:247], v[2:5]
	s_barrier
	s_setprio 0
	s_add_i32 s65, 0, 0x18000
	s_add_i32 s68, 0, 0x1c000
	v_add_u32_e32 v172, s65, v182
	v_add_u32_e32 v200, s68, v182
	ds_read_b128 v[122:125], v172
	ds_read_b128 v[126:129], v172 offset:1024
	ds_read_b128 v[130:133], v172 offset:2048
	ds_read_b128 v[172:175], v172 offset:3072
	ds_read_b128 v[176:179], v200
	ds_read_b128 v[192:195], v200 offset:1024
	ds_read_b128 v[196:199], v200 offset:2048
	ds_read_b128 v[200:203], v200 offset:3072
	s_add_u32 s28, s28, 0x100000
	s_addc_u32 s29, s29, 0
	s_mov_b32 m0, s12
	v_lshl_add_u64 v[210:211], s[28:29], 0, v[146:147]
	ds_read_b128 v[204:207], v191 offset:32768
	ds_read_b128 v[220:223], v191 offset:33792
	ds_read_b128 v[224:227], v191 offset:34816
	ds_read_b128 v[228:231], v191 offset:35840
	ds_read_b128 v[232:235], v191 offset:36864
	ds_read_b128 v[236:239], v191 offset:37888
	ds_read_b128 v[240:243], v191 offset:38912
	ds_read_b128 v[244:247], v191 offset:39936
	global_load_lds_dwordx4 v[210:211], off
	v_lshl_add_u64 v[210:211], s[28:29], 0, v[144:145]
	s_mov_b32 m0, s13
	s_nop 0
	global_load_lds_dwordx4 v[210:211], off
	s_waitcnt vmcnt(8)
	s_waitcnt lgkmcnt(0)
	s_setprio 3
	s_barrier
	v_mfma_f32_16x16x32_bf16 v[118:121], v[122:125], v[204:207], v[118:121]
	v_mfma_f32_16x16x32_bf16 v[138:141], v[130:133], v[204:207], v[138:141]
	v_mfma_f32_16x16x32_bf16 v[102:105], v[122:125], v[224:227], v[102:105]
	v_mfma_f32_16x16x32_bf16 v[114:117], v[130:133], v[224:227], v[114:117]
	v_mfma_f32_16x16x32_bf16 v[86:89], v[122:125], v[232:235], v[86:89]
	v_mfma_f32_16x16x32_bf16 v[98:101], v[130:133], v[232:235], v[98:101]
	v_mfma_f32_16x16x32_bf16 v[70:73], v[122:125], v[240:243], v[70:73]
	v_mfma_f32_16x16x32_bf16 v[82:85], v[130:133], v[240:243], v[82:85]
	v_mfma_f32_16x16x32_bf16 v[118:121], v[126:129], v[220:223], v[118:121]
	v_mfma_f32_16x16x32_bf16 v[138:141], v[172:175], v[220:223], v[138:141]
	v_mfma_f32_16x16x32_bf16 v[102:105], v[126:129], v[228:231], v[102:105]
	v_mfma_f32_16x16x32_bf16 v[114:117], v[172:175], v[228:231], v[114:117]
	v_mfma_f32_16x16x32_bf16 v[86:89], v[126:129], v[236:239], v[86:89]
	v_mfma_f32_16x16x32_bf16 v[98:101], v[172:175], v[236:239], v[98:101]
	v_mfma_f32_16x16x32_bf16 v[70:73], v[126:129], v[244:247], v[70:73]
	v_mfma_f32_16x16x32_bf16 v[82:85], v[172:175], v[244:247], v[82:85]
	v_mfma_f32_16x16x32_bf16 v[134:137], v[176:179], v[204:207], v[134:137]
	v_mfma_f32_16x16x32_bf16 v[110:113], v[196:199], v[204:207], v[110:113]
	v_mfma_f32_16x16x32_bf16 v[106:109], v[176:179], v[224:227], v[106:109]
	v_mfma_f32_16x16x32_bf16 v[94:97], v[196:199], v[224:227], v[94:97]
	v_mfma_f32_16x16x32_bf16 v[90:93], v[176:179], v[232:235], v[90:93]
	v_mfma_f32_16x16x32_bf16 v[78:81], v[196:199], v[232:235], v[78:81]
	v_mfma_f32_16x16x32_bf16 v[74:77], v[176:179], v[240:243], v[74:77]
	v_mfma_f32_16x16x32_bf16 v[66:69], v[196:199], v[240:243], v[66:69]
	v_mfma_f32_16x16x32_bf16 v[134:137], v[192:195], v[220:223], v[134:137]
	v_mfma_f32_16x16x32_bf16 v[110:113], v[200:203], v[220:223], v[110:113]
	v_mfma_f32_16x16x32_bf16 v[106:109], v[192:195], v[228:231], v[106:109]
	v_mfma_f32_16x16x32_bf16 v[94:97], v[200:203], v[228:231], v[94:97]
	v_mfma_f32_16x16x32_bf16 v[90:93], v[192:195], v[236:239], v[90:93]
	v_mfma_f32_16x16x32_bf16 v[78:81], v[200:203], v[236:239], v[78:81]
	v_mfma_f32_16x16x32_bf16 v[74:77], v[192:195], v[244:247], v[74:77]
	v_mfma_f32_16x16x32_bf16 v[66:69], v[200:203], v[244:247], v[66:69]
	s_barrier
; #define PG8_STAGE(bufoff, gbase, voff) do { _Pragma("unroll") for (int _i = 0; _i < 2; ++_i) \
;         __builtin_amdgcn_global_load_lds((const unsigned*)((const char*)(gbase) + (voff)[_i]), (PG8_LAS unsigned*)(lds + (bufoff) + ldsw + _i * 8192), 16, 0, 0); } while (0)
; #define PG8_LDA(dst, b, h) do { _Pragma("unroll") for (int m = 0; m < 4; ++m) _Pragma("unroll") for (int k = 0; k < 2; ++k) dst[m][k] = *(const PG8_LAS bf16x8*)(lds + PG8_SA(b, h) + aoff + m * 2048 + k * 1024); } while (0)
; #define PG8_MMA(ai, bj, At, Bt) do { __builtin_amdgcn_s_setprio(1); _Pragma("unroll") for (int m = 0; m < 4; ++m) _Pragma("unroll") for (int n = 0; n < 2; ++n) _Pragma("unroll") for (int k = 0; k < 2; ++k) \
;         acc[ai][bj][m][n] = __builtin_amdgcn_mfma_f32_16x16x32_bf16(Bt[n][k], At[m][k], acc[ai][bj][m][n], 0, 0, 0); __builtin_amdgcn_s_setprio(0); } while (0)
; #define PG8_WAIT_V(n) asm volatile("s_waitcnt vmcnt(" #n ")" ::: "memory")
; #define PG8_WAIT_L(n) asm volatile("s_waitcnt lgkmcnt(" #n ")" ::: "memory")
; #define PG8_BAR __builtin_amdgcn_s_barrier()
; #define PG8_SCHED __builtin_amdgcn_sched_barrier(0)
; template <class Epi, class Sched, bool ALIGN_EPI = false, bool SP2 = false>
; __device__ __forceinline__ void gemm_phase(PG8_LAS unsigned char* lds, const Gemm g, const Sched& S, const Epi& E) {
;     ...
;             PG8_WAIT_V(8); PG8_WAIT_L(0); PG8_BAR; PG8_MMA(0, 0, At, B0); PG8_MMA(0, 1, At, B1); PG8_BAR; PG8_SCHED;
;             PG8_LDA(At, 1, 1); PG8_STAGE(PG8_SB(1, 0), b3, voffB); PG8_STAGE(PG8_SB(1, 1), b3 + hstep, voffB); PG8_STAGE(PG8_SA(1, 0), a3, voffA);
;             PG8_WAIT_V(8); PG8_WAIT_L(0); PG8_BAR; PG8_MMA(1, 0, At, B0); PG8_MMA(1, 1, At, B1); PG8_BAR; PG8_SCHED;
	s_setprio 0
	s_add_i32 s28, s65, s9
	v_lshl_add_u64 v[180:181], v[180:181], 0, s[96:97]
	s_mov_b32 m0, s28
	ds_read_b128 v[204:207], v191 offset:49152
	ds_read_b128 v[220:223], v191 offset:50176
	ds_read_b128 v[224:227], v191 offset:51200
	ds_read_b128 v[228:231], v191 offset:52224
	ds_read_b128 v[232:235], v191 offset:53248
	ds_read_b128 v[236:239], v191 offset:54272
	ds_read_b128 v[240:243], v191 offset:55296
	ds_read_b128 v[244:247], v191 offset:56320
	global_load_lds_dwordx4 v[180:181], off
	s_add_i32 m0, s28, 0x2000
	s_add_u32 s26, s26, 0x100080
	v_lshl_add_u64 v[180:181], v[208:209], 0, s[96:97]
	s_addc_u32 s27, s27, 0
	s_add_i32 s28, s68, s9
	global_load_lds_dwordx4 v[180:181], off
	v_lshl_add_u64 v[180:181], s[26:27], 0, v[158:159]
	s_mov_b32 m0, s28
	v_lshl_add_u64 v[170:171], v[170:171], 0, s[96:97]
	global_load_lds_dwordx4 v[180:181], off
	v_lshl_add_u64 v[180:181], s[26:27], 0, v[142:143]
	s_add_i32 m0, s28, 0x2000
	s_nop 0
	global_load_lds_dwordx4 v[180:181], off
	v_lshl_add_u64 v[180:181], v[248:249], 0, s[96:97]
	s_mov_b32 m0, s0
	s_nop 0
	global_load_lds_dwordx4 v[180:181], off
	s_mov_b32 m0, s34
	s_nop 0
	global_load_lds_dwordx4 v[170:171], off
	s_waitcnt vmcnt(8)
	s_waitcnt lgkmcnt(0)
	s_setprio 3
	s_barrier
	v_mfma_f32_16x16x32_bf16 v[54:57], v[122:125], v[204:207], v[54:57]
	v_mfma_f32_16x16x32_bf16 v[62:65], v[130:133], v[204:207], v[62:65]
	v_mfma_f32_16x16x32_bf16 v[38:41], v[122:125], v[224:227], v[38:41]
	v_mfma_f32_16x16x32_bf16 v[50:53], v[130:133], v[224:227], v[50:53]
	v_mfma_f32_16x16x32_bf16 v[22:25], v[122:125], v[232:235], v[22:25]
	v_mfma_f32_16x16x32_bf16 v[34:37], v[130:133], v[232:235], v[34:37]
	v_mfma_f32_16x16x32_bf16 v[6:9], v[122:125], v[240:243], v[6:9]
	v_mfma_f32_16x16x32_bf16 v[18:21], v[130:133], v[240:243], v[18:21]
	v_mfma_f32_16x16x32_bf16 v[54:57], v[126:129], v[220:223], v[54:57]
	v_mfma_f32_16x16x32_bf16 v[62:65], v[172:175], v[220:223], v[62:65]
	v_mfma_f32_16x16x32_bf16 v[38:41], v[126:129], v[228:231], v[38:41]
	v_mfma_f32_16x16x32_bf16 v[50:53], v[172:175], v[228:231], v[50:53]
	v_mfma_f32_16x16x32_bf16 v[22:25], v[126:129], v[236:239], v[22:25]
	v_mfma_f32_16x16x32_bf16 v[34:37], v[172:175], v[236:239], v[34:37]
	v_mfma_f32_16x16x32_bf16 v[6:9], v[126:129], v[244:247], v[6:9]
	v_mfma_f32_16x16x32_bf16 v[18:21], v[172:175], v[244:247], v[18:21]
	v_mfma_f32_16x16x32_bf16 v[58:61], v[176:179], v[204:207], v[58:61]
	v_mfma_f32_16x16x32_bf16 v[46:49], v[196:199], v[204:207], v[46:49]
	v_mfma_f32_16x16x32_bf16 v[42:45], v[176:179], v[224:227], v[42:45]
	v_mfma_f32_16x16x32_bf16 v[30:33], v[196:199], v[224:227], v[30:33]
	v_mfma_f32_16x16x32_bf16 v[26:29], v[176:179], v[232:235], v[26:29]
	v_mfma_f32_16x16x32_bf16 v[14:17], v[196:199], v[232:235], v[14:17]
	v_mfma_f32_16x16x32_bf16 v[10:13], v[176:179], v[240:243], v[10:13]
	v_mfma_f32_16x16x32_bf16 v[2:5], v[196:199], v[240:243], v[2:5]
	v_mfma_f32_16x16x32_bf16 v[58:61], v[192:195], v[220:223], v[58:61]
	v_mfma_f32_16x16x32_bf16 v[46:49], v[200:203], v[220:223], v[46:49]
	v_mfma_f32_16x16x32_bf16 v[42:45], v[192:195], v[228:231], v[42:45]
	v_mfma_f32_16x16x32_bf16 v[30:33], v[200:203], v[228:231], v[30:33]
	v_mfma_f32_16x16x32_bf16 v[26:29], v[192:195], v[236:239], v[26:29]
	v_mfma_f32_16x16x32_bf16 v[14:17], v[200:203], v[236:239], v[14:17]
	v_mfma_f32_16x16x32_bf16 v[10:13], v[192:195], v[244:247], v[10:13]
	v_mfma_f32_16x16x32_bf16 v[2:5], v[200:203], v[244:247], v[2:5]
	s_barrier
	s_setprio 0
	s_add_i32 s17, s17, 2
	s_add_u32 vcc_lo, vcc_lo, 0x100
	s_addc_u32 s16, s16, 0
	s_add_u32 s62, s62, 0x100
	s_addc_u32 s63, s63, 0
	s_cmp_gt_u32 s17, 61
	s_cbranch_scc0 .LBB0_124
	s_and_b64 vcc, exec, s[46:47]
	s_cbranch_vccz .LBB0_127
	s_barrier

; #define PG8_STAGE(bufoff, gbase, voff) do { _Pragma("unroll") for (int _i = 0; _i < 2; ++_i) \
;         __builtin_amdgcn_global_load_lds((const unsigned*)((const char*)(gbase) + (voff)[_i]), (PG8_LAS unsigned*)(lds + (bufoff) + ldsw + _i * 8192), 16, 0, 0); } while (0)
; #define PG8_LDA(dst, b, h) do { _Pragma("unroll") for (int m = 0; m < 4; ++m) _Pragma("unroll") for (int k = 0; k < 2; ++k) dst[m][k] = *(const PG8_LAS bf16x8*)(lds + PG8_SA(b, h) + aoff + m * 2048 + k * 1024); } while (0)
; #define PG8_LDB(dst, b, h) do { _Pragma("unroll") for (int n = 0; n < 2; ++n) _Pragma("unroll") for (int k = 0; k < 2; ++k) dst[n][k] = *(const PG8_LAS bf16x8*)(lds + PG8_SB(b, h) + boff + n * 2048 + k * 1024); } while (0)
; #define PG8_MMA(ai, bj, At, Bt) do { __builtin_amdgcn_s_setprio(1); _Pragma("unroll") for (int m = 0; m < 4; ++m) _Pragma("unroll") for (int n = 0; n < 2; ++n) _Pragma("unroll") for (int k = 0; k < 2; ++k) \
;         acc[ai][bj][m][n] = __builtin_amdgcn_mfma_f32_16x16x32_bf16(Bt[n][k], At[m][k], acc[ai][bj][m][n], 0, 0, 0); __builtin_amdgcn_s_setprio(0); } while (0)
; #define PG8_WAIT_V(n) asm volatile("s_waitcnt vmcnt(" #n ")" ::: "memory")
; #define PG8_BAR __builtin_amdgcn_s_barrier()
; template <class Epi, class Sched, bool ALIGN_EPI = false, bool SP2 = false>
; __device__ __forceinline__ void gemm_phase(PG8_LAS unsigned char* lds, const Gemm g, const Sched& S, const Epi& E) {
;     ...
;         for (int t = 0; t < nt; t += 2) {
;             const bool last = (t == nt - 2);
;             const char* a1 = cA + (size_t)(t + 1) * kstep;
;             const char* a2 = last ? nA : cA + (size_t)(t + 2) * kstep; const char* b2 = last ? nB : cB + (size_t)(t + 2) * kstep;
;             const char* a3 = a2 + kstep; const char* b3 = b2 + kstep;
;             if (last && has_next) S.a_ready(nxt);
;             if constexpr (SP2) {
;             PG8_LDB(B0, 0, 0); PG8_LDB(B1, 0, 1); PG8_SCHED; PG8_LDA(At, 0, 0); PG8_STAGE(PG8_SA(1, 1), a1 + hstep, voffA);
;             PG8_WAIT_V(8); PG8_WAIT_L(0); PG8_BAR; PG8_MMA(0, 0, At, B0); PG8_MMA(0, 1, At, B1); PG8_BAR; PG8_SCHED;
;             PG8_LDA(At, 0, 1); PG8_STAGE(PG8_SB(0, 0), b2, voffB); PG8_STAGE(PG8_SB(0, 1), b2 + hstep, voffB); PG8_STAGE(PG8_SA(0, 0), a2, voffA);
;             PG8_WAIT_V(8); PG8_WAIT_L(0); PG8_BAR; PG8_MMA(1, 0, At, B0); PG8_MMA(1, 1, At, B1); PG8_BAR; PG8_SCHED;
.LBB0_419:
	s_add_u32 s26, s48, 0xfff80080
	s_addc_u32 s27, s49, -1
	s_add_i32 s39, 0, 0x10000
	s_cmp_eq_u32 s17, 28
	s_cselect_b32 s29, s15, s27
	s_cselect_b32 s28, s30, s26
	s_cselect_b32 s27, s31, s16
	s_cselect_b32 s26, s34, s35
	s_add_i32 s41, 0, 0x14000
	v_add_u32_e32 v142, s39, v190
	v_add_u32_e32 v170, s41, v190
	ds_read_b128 v[130:133], v142
	ds_read_b128 v[134:137], v142 offset:1024
	ds_read_b128 v[138:141], v142 offset:2048
	ds_read_b128 v[142:145], v142 offset:3072
	ds_read_b128 v[146:149], v170
	ds_read_b128 v[150:153], v170 offset:1024
	ds_read_b128 v[178:181], v170 offset:2048
	ds_read_b128 v[182:185], v170 offset:3072
	v_lshl_add_u64 v[170:171], s[48:49], 0, v[176:177]
	s_add_i32 m0, s6, 0xc000
	ds_read_b128 v[186:189], v192
	ds_read_b128 v[194:197], v192 offset:1024
	ds_read_b128 v[198:201], v192 offset:2048
	ds_read_b128 v[202:205], v192 offset:3072
	ds_read_b128 v[206:209], v192 offset:4096
	ds_read_b128 v[220:223], v192 offset:5120
	ds_read_b128 v[224:227], v192 offset:6144
	ds_read_b128 v[228:231], v192 offset:7168
	global_load_lds_dwordx4 v[170:171], off
	v_lshl_add_u64 v[170:171], s[48:49], 0, v[174:175]
	s_add_i32 m0, s6, 0xe000
	s_nop 0
	global_load_lds_dwordx4 v[170:171], off
	s_waitcnt vmcnt(8)
	s_waitcnt lgkmcnt(0)
	s_setprio 3
	s_barrier
	v_mfma_f32_16x16x32_bf16 v[126:129], v[130:133], v[186:189], v[126:129]
	v_mfma_f32_16x16x32_bf16 v[122:125], v[138:141], v[186:189], v[122:125]
	v_mfma_f32_16x16x32_bf16 v[110:113], v[130:133], v[198:201], v[110:113]
	v_mfma_f32_16x16x32_bf16 v[106:109], v[138:141], v[198:201], v[106:109]
	v_mfma_f32_16x16x32_bf16 v[94:97], v[130:133], v[206:209], v[94:97]
	v_mfma_f32_16x16x32_bf16 v[90:93], v[138:141], v[206:209], v[90:93]
	v_mfma_f32_16x16x32_bf16 v[78:81], v[130:133], v[224:227], v[78:81]
	v_mfma_f32_16x16x32_bf16 v[74:77], v[138:141], v[224:227], v[74:77]
	v_mfma_f32_16x16x32_bf16 v[126:129], v[134:137], v[194:197], v[126:129]
	v_mfma_f32_16x16x32_bf16 v[122:125], v[142:145], v[194:197], v[122:125]
	v_mfma_f32_16x16x32_bf16 v[110:113], v[134:137], v[202:205], v[110:113]
	v_mfma_f32_16x16x32_bf16 v[106:109], v[142:145], v[202:205], v[106:109]
	v_mfma_f32_16x16x32_bf16 v[94:97], v[134:137], v[220:223], v[94:97]
	v_mfma_f32_16x16x32_bf16 v[90:93], v[142:145], v[220:223], v[90:93]
	v_mfma_f32_16x16x32_bf16 v[78:81], v[134:137], v[228:231], v[78:81]
	v_mfma_f32_16x16x32_bf16 v[74:77], v[142:145], v[228:231], v[74:77]
	v_mfma_f32_16x16x32_bf16 v[118:121], v[146:149], v[186:189], v[118:121]
	v_mfma_f32_16x16x32_bf16 v[114:117], v[178:181], v[186:189], v[114:117]
	v_mfma_f32_16x16x32_bf16 v[102:105], v[146:149], v[198:201], v[102:105]
	v_mfma_f32_16x16x32_bf16 v[98:101], v[178:181], v[198:201], v[98:101]
	v_mfma_f32_16x16x32_bf16 v[86:89], v[146:149], v[206:209], v[86:89]
	v_mfma_f32_16x16x32_bf16 v[82:85], v[178:181], v[206:209], v[82:85]
	v_mfma_f32_16x16x32_bf16 v[70:73], v[146:149], v[224:227], v[70:73]
	v_mfma_f32_16x16x32_bf16 v[66:69], v[178:181], v[224:227], v[66:69]
	v_mfma_f32_16x16x32_bf16 v[118:121], v[150:153], v[194:197], v[118:121]
	v_mfma_f32_16x16x32_bf16 v[114:117], v[182:185], v[194:197], v[114:117]
	v_mfma_f32_16x16x32_bf16 v[102:105], v[150:153], v[202:205], v[102:105]
	v_mfma_f32_16x16x32_bf16 v[98:101], v[182:185], v[202:205], v[98:101]
	v_mfma_f32_16x16x32_bf16 v[86:89], v[150:153], v[220:223], v[86:89]
	v_mfma_f32_16x16x32_bf16 v[82:85], v[182:185], v[220:223], v[82:85]
	v_mfma_f32_16x16x32_bf16 v[70:73], v[150:153], v[228:231], v[70:73]
	v_mfma_f32_16x16x32_bf16 v[66:69], v[182:185], v[228:231], v[66:69]
	s_barrier
	s_setprio 0
	s_add_i32 s39, s39, s5
	v_lshl_add_u64 v[170:171], s[26:27], 0, v[158:159]
	s_mov_b32 m0, s39
	ds_read_b128 v[186:189], v192 offset:16384
	ds_read_b128 v[194:197], v192 offset:17408
	ds_read_b128 v[198:201], v192 offset:18432
	ds_read_b128 v[202:205], v192 offset:19456
	ds_read_b128 v[206:209], v192 offset:20480
	ds_read_b128 v[220:223], v192 offset:21504
	ds_read_b128 v[224:227], v192 offset:22528
	ds_read_b128 v[228:231], v192 offset:23552
	global_load_lds_dwordx4 v[170:171], off
	s_add_i32 m0, s39, 0x2000
	s_add_u32 s50, s26, 0x80000
	v_lshl_add_u64 v[210:211], s[26:27], 0, v[154:155]
	s_addc_u32 s51, s27, 0
	s_add_i32 s39, s41, s5
	global_load_lds_dwordx4 v[210:211], off
	v_lshl_add_u64 v[232:233], s[50:51], 0, v[158:159]
	s_mov_b32 m0, s39
	v_lshl_add_u64 v[234:235], s[28:29], 0, v[156:157]
	global_load_lds_dwordx4 v[232:233], off
	v_lshl_add_u64 v[232:233], s[50:51], 0, v[154:155]
	s_add_i32 m0, s39, 0x2000
	s_nop 0
	global_load_lds_dwordx4 v[232:233], off
	v_lshl_add_u64 v[232:233], s[28:29], 0, v[172:173]
	s_mov_b32 m0, s6
	s_nop 0
	global_load_lds_dwordx4 v[232:233], off
	s_mov_b32 m0, s7
	s_nop 0
	global_load_lds_dwordx4 v[234:235], off
	s_waitcnt vmcnt(8)
	s_waitcnt lgkmcnt(0)
	s_setprio 3
	s_barrier
; #define PG8_STAGE(bufoff, gbase, voff) do { _Pragma("unroll") for (int _i = 0; _i < 2; ++_i) \
;         __builtin_amdgcn_global_load_lds((const unsigned*)((const char*)(gbase) + (voff)[_i]), (PG8_LAS unsigned*)(lds + (bufoff) + ldsw + _i * 8192), 16, 0, 0); } while (0)
; #define PG8_LDA(dst, b, h) do { _Pragma("unroll") for (int m = 0; m < 4; ++m) _Pragma("unroll") for (int k = 0; k < 2; ++k) dst[m][k] = *(const PG8_LAS bf16x8*)(lds + PG8_SA(b, h) + aoff + m * 2048 + k * 1024); } while (0)
; #define PG8_LDB(dst, b, h) do { _Pragma("unroll") for (int n = 0; n < 2; ++n) _Pragma("unroll") for (int k = 0; k < 2; ++k) dst[n][k] = *(const PG8_LAS bf16x8*)(lds + PG8_SB(b, h) + boff + n * 2048 + k * 1024); } while (0)
; #define PG8_MMA(ai, bj, At, Bt) do { __builtin_amdgcn_s_setprio(1); _Pragma("unroll") for (int m = 0; m < 4; ++m) _Pragma("unroll") for (int n = 0; n < 2; ++n) _Pragma("unroll") for (int k = 0; k < 2; ++k) \
;         acc[ai][bj][m][n] = __builtin_amdgcn_mfma_f32_16x16x32_bf16(Bt[n][k], At[m][k], acc[ai][bj][m][n], 0, 0, 0); __builtin_amdgcn_s_setprio(0); } while (0)
; #define PG8_WAIT_V(n) asm volatile("s_waitcnt vmcnt(" #n ")" ::: "memory")
; #define PG8_WAIT_L(n) asm volatile("s_waitcnt lgkmcnt(" #n ")" ::: "memory")
; #define PG8_BAR __builtin_amdgcn_s_barrier()
; #define PG8_SCHED __builtin_amdgcn_sched_barrier(0)
; template <class Epi, class Sched, bool ALIGN_EPI = false, bool SP2 = false>
; __device__ __forceinline__ void gemm_phase(PG8_LAS unsigned char* lds, const Gemm g, const Sched& S, const Epi& E) {
;     ...
;             PG8_WAIT_V(8); PG8_WAIT_L(0); PG8_BAR; PG8_MMA(1, 0, At, B0); PG8_MMA(1, 1, At, B1); PG8_BAR; PG8_SCHED;
;             PG8_LDB(B0, 1, 0); PG8_LDB(B1, 1, 1); PG8_SCHED; PG8_LDA(At, 1, 0); PG8_STAGE(PG8_SA(0, 1), a2 + hstep, voffA);
;             PG8_WAIT_V(8); PG8_WAIT_L(0); PG8_BAR; PG8_MMA(0, 0, At, B0); PG8_MMA(0, 1, At, B1); PG8_BAR; PG8_SCHED;
	v_mfma_f32_16x16x32_bf16 v[62:65], v[130:133], v[186:189], v[62:65]
	v_mfma_f32_16x16x32_bf16 v[58:61], v[138:141], v[186:189], v[58:61]
	v_mfma_f32_16x16x32_bf16 v[46:49], v[130:133], v[198:201], v[46:49]
	v_mfma_f32_16x16x32_bf16 v[42:45], v[138:141], v[198:201], v[42:45]
	v_mfma_f32_16x16x32_bf16 v[30:33], v[130:133], v[206:209], v[30:33]
	v_mfma_f32_16x16x32_bf16 v[26:29], v[138:141], v[206:209], v[26:29]
	v_mfma_f32_16x16x32_bf16 v[14:17], v[130:133], v[224:227], v[14:17]
	v_mfma_f32_16x16x32_bf16 v[10:13], v[138:141], v[224:227], v[10:13]
	v_mfma_f32_16x16x32_bf16 v[62:65], v[134:137], v[194:197], v[62:65]
	v_mfma_f32_16x16x32_bf16 v[58:61], v[142:145], v[194:197], v[58:61]
	v_mfma_f32_16x16x32_bf16 v[46:49], v[134:137], v[202:205], v[46:49]
	v_mfma_f32_16x16x32_bf16 v[42:45], v[142:145], v[202:205], v[42:45]
	v_mfma_f32_16x16x32_bf16 v[30:33], v[134:137], v[220:223], v[30:33]
	v_mfma_f32_16x16x32_bf16 v[26:29], v[142:145], v[220:223], v[26:29]
	v_mfma_f32_16x16x32_bf16 v[14:17], v[134:137], v[228:231], v[14:17]
	v_mfma_f32_16x16x32_bf16 v[10:13], v[142:145], v[228:231], v[10:13]
	v_mfma_f32_16x16x32_bf16 v[54:57], v[146:149], v[186:189], v[54:57]
	v_mfma_f32_16x16x32_bf16 v[50:53], v[178:181], v[186:189], v[50:53]
	v_mfma_f32_16x16x32_bf16 v[38:41], v[146:149], v[198:201], v[38:41]
	v_mfma_f32_16x16x32_bf16 v[34:37], v[178:181], v[198:201], v[34:37]
	v_mfma_f32_16x16x32_bf16 v[22:25], v[146:149], v[206:209], v[22:25]
	v_mfma_f32_16x16x32_bf16 v[18:21], v[178:181], v[206:209], v[18:21]
	v_mfma_f32_16x16x32_bf16 v[6:9], v[146:149], v[224:227], v[6:9]
	v_mfma_f32_16x16x32_bf16 v[2:5], v[178:181], v[224:227], v[2:5]
	v_mfma_f32_16x16x32_bf16 v[54:57], v[150:153], v[194:197], v[54:57]
	v_mfma_f32_16x16x32_bf16 v[50:53], v[182:185], v[194:197], v[50:53]
	v_mfma_f32_16x16x32_bf16 v[38:41], v[150:153], v[202:205], v[38:41]
	v_mfma_f32_16x16x32_bf16 v[34:37], v[182:185], v[202:205], v[34:37]
	v_mfma_f32_16x16x32_bf16 v[22:25], v[150:153], v[220:223], v[22:25]
	v_mfma_f32_16x16x32_bf16 v[18:21], v[182:185], v[220:223], v[18:21]
	v_mfma_f32_16x16x32_bf16 v[6:9], v[150:153], v[228:231], v[6:9]
	v_mfma_f32_16x16x32_bf16 v[2:5], v[182:185], v[228:231], v[2:5]
	s_barrier
	s_setprio 0
	s_add_i32 s39, 0, 0x18000
	s_add_i32 s41, 0, 0x1c000
	v_add_u32_e32 v142, s39, v190
	v_add_u32_e32 v182, s41, v190
	ds_read_b128 v[130:133], v142
	ds_read_b128 v[134:137], v142 offset:1024
	ds_read_b128 v[138:141], v142 offset:2048
	ds_read_b128 v[142:145], v142 offset:3072
	ds_read_b128 v[146:149], v182
	ds_read_b128 v[150:153], v182 offset:1024
	ds_read_b128 v[178:181], v182 offset:2048
	ds_read_b128 v[182:185], v182 offset:3072
	s_add_u32 s28, s28, 0x80000
	s_addc_u32 s29, s29, 0
	s_mov_b32 m0, s8
	v_lshl_add_u64 v[236:237], s[28:29], 0, v[172:173]
	ds_read_b128 v[186:189], v192 offset:32768
	ds_read_b128 v[194:197], v192 offset:33792
	ds_read_b128 v[198:201], v192 offset:34816
	ds_read_b128 v[202:205], v192 offset:35840
	ds_read_b128 v[206:209], v192 offset:36864
	ds_read_b128 v[220:223], v192 offset:37888
	ds_read_b128 v[224:227], v192 offset:38912
	ds_read_b128 v[228:231], v192 offset:39936
	global_load_lds_dwordx4 v[236:237], off
	v_lshl_add_u64 v[236:237], s[28:29], 0, v[156:157]
	s_mov_b32 m0, s9
	s_nop 0
	global_load_lds_dwordx4 v[236:237], off
	s_waitcnt vmcnt(8)
	s_waitcnt lgkmcnt(0)
	s_setprio 3
	s_barrier
	v_mfma_f32_16x16x32_bf16 v[126:129], v[130:133], v[186:189], v[126:129]
	v_mfma_f32_16x16x32_bf16 v[122:125], v[138:141], v[186:189], v[122:125]
	v_mfma_f32_16x16x32_bf16 v[110:113], v[130:133], v[198:201], v[110:113]
	v_mfma_f32_16x16x32_bf16 v[106:109], v[138:141], v[198:201], v[106:109]
	v_mfma_f32_16x16x32_bf16 v[94:97], v[130:133], v[206:209], v[94:97]
	v_mfma_f32_16x16x32_bf16 v[90:93], v[138:141], v[206:209], v[90:93]
	v_mfma_f32_16x16x32_bf16 v[78:81], v[130:133], v[224:227], v[78:81]
	v_mfma_f32_16x16x32_bf16 v[74:77], v[138:141], v[224:227], v[74:77]
	v_mfma_f32_16x16x32_bf16 v[126:129], v[134:137], v[194:197], v[126:129]
	v_mfma_f32_16x16x32_bf16 v[122:125], v[142:145], v[194:197], v[122:125]
	v_mfma_f32_16x16x32_bf16 v[110:113], v[134:137], v[202:205], v[110:113]
	v_mfma_f32_16x16x32_bf16 v[106:109], v[142:145], v[202:205], v[106:109]
	v_mfma_f32_16x16x32_bf16 v[94:97], v[134:137], v[220:223], v[94:97]
	v_mfma_f32_16x16x32_bf16 v[90:93], v[142:145], v[220:223], v[90:93]
	v_mfma_f32_16x16x32_bf16 v[78:81], v[134:137], v[228:231], v[78:81]
	v_mfma_f32_16x16x32_bf16 v[74:77], v[142:145], v[228:231], v[74:77]
	v_mfma_f32_16x16x32_bf16 v[118:121], v[146:149], v[186:189], v[118:121]
	v_mfma_f32_16x16x32_bf16 v[114:117], v[178:181], v[186:189], v[114:117]
	v_mfma_f32_16x16x32_bf16 v[102:105], v[146:149], v[198:201], v[102:105]
	v_mfma_f32_16x16x32_bf16 v[98:101], v[178:181], v[198:201], v[98:101]
	v_mfma_f32_16x16x32_bf16 v[86:89], v[146:149], v[206:209], v[86:89]
	v_mfma_f32_16x16x32_bf16 v[82:85], v[178:181], v[206:209], v[82:85]
	v_mfma_f32_16x16x32_bf16 v[70:73], v[146:149], v[224:227], v[70:73]
	v_mfma_f32_16x16x32_bf16 v[66:69], v[178:181], v[224:227], v[66:69]
	v_mfma_f32_16x16x32_bf16 v[118:121], v[150:153], v[194:197], v[118:121]
	v_mfma_f32_16x16x32_bf16 v[114:117], v[182:185], v[194:197], v[114:117]
	v_mfma_f32_16x16x32_bf16 v[102:105], v[150:153], v[202:205], v[102:105]
	v_mfma_f32_16x16x32_bf16 v[98:101], v[182:185], v[202:205], v[98:101]
	v_mfma_f32_16x16x32_bf16 v[86:89], v[150:153], v[220:223], v[86:89]
	v_mfma_f32_16x16x32_bf16 v[82:85], v[182:185], v[220:223], v[82:85]
	v_mfma_f32_16x16x32_bf16 v[70:73], v[150:153], v[228:231], v[70:73]
	v_mfma_f32_16x16x32_bf16 v[66:69], v[182:185], v[228:231], v[66:69]
	s_barrier
; #define PG8_STAGE(bufoff, gbase, voff) do { _Pragma("unroll") for (int _i = 0; _i < 2; ++_i) \
;         __builtin_amdgcn_global_load_lds((const unsigned*)((const char*)(gbase) + (voff)[_i]), (PG8_LAS unsigned*)(lds + (bufoff) + ldsw + _i * 8192), 16, 0, 0); } while (0)
; #define PG8_LDA(dst, b, h) do { _Pragma("unroll") for (int m = 0; m < 4; ++m) _Pragma("unroll") for (int k = 0; k < 2; ++k) dst[m][k] = *(const PG8_LAS bf16x8*)(lds + PG8_SA(b, h) + aoff + m * 2048 + k * 1024); } while (0)
; #define PG8_MMA(ai, bj, At, Bt) do { __builtin_amdgcn_s_setprio(1); _Pragma("unroll") for (int m = 0; m < 4; ++m) _Pragma("unroll") for (int n = 0; n < 2; ++n) _Pragma("unroll") for (int k = 0; k < 2; ++k) \
;         acc[ai][bj][m][n] = __builtin_amdgcn_mfma_f32_16x16x32_bf16(Bt[n][k], At[m][k], acc[ai][bj][m][n], 0, 0, 0); __builtin_amdgcn_s_setprio(0); } while (0)
; #define PG8_WAIT_V(n) asm volatile("s_waitcnt vmcnt(" #n ")" ::: "memory")
; #define PG8_WAIT_L(n) asm volatile("s_waitcnt lgkmcnt(" #n ")" ::: "memory")
; #define PG8_BAR __builtin_amdgcn_s_barrier()
; #define PG8_SCHED __builtin_amdgcn_sched_barrier(0)
; template <class Epi, class Sched, bool ALIGN_EPI = false, bool SP2 = false>
; __device__ __forceinline__ void gemm_phase(PG8_LAS unsigned char* lds, const Gemm g, const Sched& S, const Epi& E) {
;     ...
;             PG8_WAIT_V(8); PG8_WAIT_L(0); PG8_BAR; PG8_MMA(0, 0, At, B0); PG8_MMA(0, 1, At, B1); PG8_BAR; PG8_SCHED;
;             PG8_LDA(At, 1, 1); PG8_STAGE(PG8_SB(1, 0), b3, voffB); PG8_STAGE(PG8_SB(1, 1), b3 + hstep, voffB); PG8_STAGE(PG8_SA(1, 0), a3, voffA);
;             PG8_WAIT_V(8); PG8_WAIT_L(0); PG8_BAR; PG8_MMA(1, 0, At, B0); PG8_MMA(1, 1, At, B1); PG8_BAR; PG8_SCHED;
	s_setprio 0
	s_add_i32 s28, s39, s5
	v_lshl_add_u64 v[170:171], v[170:171], 0, s[96:97]
	s_mov_b32 m0, s28
	ds_read_b128 v[186:189], v192 offset:49152
	ds_read_b128 v[194:197], v192 offset:50176
	ds_read_b128 v[198:201], v192 offset:51200
	ds_read_b128 v[202:205], v192 offset:52224
	ds_read_b128 v[206:209], v192 offset:53248
	ds_read_b128 v[220:223], v192 offset:54272
	ds_read_b128 v[224:227], v192 offset:55296
	ds_read_b128 v[228:231], v192 offset:56320
	global_load_lds_dwordx4 v[170:171], off
	s_add_i32 m0, s28, 0x2000
	s_add_u32 s26, s26, 0x80080
	v_lshl_add_u64 v[170:171], v[210:211], 0, s[96:97]
	s_addc_u32 s27, s27, 0
	s_add_i32 s28, s41, s5
	global_load_lds_dwordx4 v[170:171], off
	v_lshl_add_u64 v[170:171], s[26:27], 0, v[158:159]
	s_mov_b32 m0, s28
	s_nop 0
	global_load_lds_dwordx4 v[170:171], off
	v_lshl_add_u64 v[170:171], s[26:27], 0, v[154:155]
	s_add_i32 m0, s28, 0x2000
	s_nop 0
	global_load_lds_dwordx4 v[170:171], off
	v_lshl_add_u64 v[170:171], v[232:233], 0, s[96:97]
	s_mov_b32 m0, s10
	s_nop 0
	global_load_lds_dwordx4 v[170:171], off
	v_lshl_add_u64 v[170:171], v[234:235], 0, s[96:97]
	s_mov_b32 m0, s11
	s_nop 0
	global_load_lds_dwordx4 v[170:171], off
	s_waitcnt vmcnt(8)
	s_waitcnt lgkmcnt(0)
	s_setprio 3
	s_barrier
	v_mfma_f32_16x16x32_bf16 v[62:65], v[130:133], v[186:189], v[62:65]
	v_mfma_f32_16x16x32_bf16 v[58:61], v[138:141], v[186:189], v[58:61]
	v_mfma_f32_16x16x32_bf16 v[46:49], v[130:133], v[198:201], v[46:49]
	v_mfma_f32_16x16x32_bf16 v[42:45], v[138:141], v[198:201], v[42:45]
	v_mfma_f32_16x16x32_bf16 v[30:33], v[130:133], v[206:209], v[30:33]
	v_mfma_f32_16x16x32_bf16 v[26:29], v[138:141], v[206:209], v[26:29]
	v_mfma_f32_16x16x32_bf16 v[14:17], v[130:133], v[224:227], v[14:17]
	v_mfma_f32_16x16x32_bf16 v[10:13], v[138:141], v[224:227], v[10:13]
	v_mfma_f32_16x16x32_bf16 v[62:65], v[134:137], v[194:197], v[62:65]
	v_mfma_f32_16x16x32_bf16 v[58:61], v[142:145], v[194:197], v[58:61]
	v_mfma_f32_16x16x32_bf16 v[46:49], v[134:137], v[202:205], v[46:49]
	v_mfma_f32_16x16x32_bf16 v[42:45], v[142:145], v[202:205], v[42:45]
	v_mfma_f32_16x16x32_bf16 v[30:33], v[134:137], v[220:223], v[30:33]
	v_mfma_f32_16x16x32_bf16 v[26:29], v[142:145], v[220:223], v[26:29]
	v_mfma_f32_16x16x32_bf16 v[14:17], v[134:137], v[228:231], v[14:17]
	v_mfma_f32_16x16x32_bf16 v[10:13], v[142:145], v[228:231], v[10:13]
	v_mfma_f32_16x16x32_bf16 v[54:57], v[146:149], v[186:189], v[54:57]
	v_mfma_f32_16x16x32_bf16 v[50:53], v[178:181], v[186:189], v[50:53]
	v_mfma_f32_16x16x32_bf16 v[38:41], v[146:149], v[198:201], v[38:41]
	v_mfma_f32_16x16x32_bf16 v[34:37], v[178:181], v[198:201], v[34:37]
	v_mfma_f32_16x16x32_bf16 v[22:25], v[146:149], v[206:209], v[22:25]
	v_mfma_f32_16x16x32_bf16 v[18:21], v[178:181], v[206:209], v[18:21]
	v_mfma_f32_16x16x32_bf16 v[6:9], v[146:149], v[224:227], v[6:9]
	v_mfma_f32_16x16x32_bf16 v[2:5], v[178:181], v[224:227], v[2:5]
	v_mfma_f32_16x16x32_bf16 v[54:57], v[150:153], v[194:197], v[54:57]
	v_mfma_f32_16x16x32_bf16 v[50:53], v[182:185], v[194:197], v[50:53]
	v_mfma_f32_16x16x32_bf16 v[38:41], v[150:153], v[202:205], v[38:41]
	v_mfma_f32_16x16x32_bf16 v[34:37], v[182:185], v[202:205], v[34:37]
	v_mfma_f32_16x16x32_bf16 v[22:25], v[150:153], v[220:223], v[22:25]
	v_mfma_f32_16x16x32_bf16 v[18:21], v[182:185], v[220:223], v[18:21]
	v_mfma_f32_16x16x32_bf16 v[6:9], v[150:153], v[228:231], v[6:9]
	v_mfma_f32_16x16x32_bf16 v[2:5], v[182:185], v[228:231], v[2:5]
	s_barrier
	s_setprio 0
	s_add_i32 s17, s17, 2
	s_add_u32 s35, s35, 0x100
	s_addc_u32 s16, s16, 0
	s_add_u32 s48, s48, 0x100
	s_addc_u32 s49, s49, 0
	s_cmp_gt_u32 s17, 29
	s_cbranch_scc0 .LBB0_419
	s_and_b64 vcc, exec, s[36:37]
	s_cbranch_vccz .LBB0_422
	s_barrier

; #define PG8_STAGE(bufoff, gbase, voff) do { _Pragma("unroll") for (int _i = 0; _i < 2; ++_i) \
;         __builtin_amdgcn_global_load_lds((const unsigned*)((const char*)(gbase) + (voff)[_i]), (PG8_LAS unsigned*)(lds + (bufoff) + ldsw + _i * 8192), 16, 0, 0); } while (0)
; #define PG8_LDA(dst, b, h) do { _Pragma("unroll") for (int m = 0; m < 4; ++m) _Pragma("unroll") for (int k = 0; k < 2; ++k) dst[m][k] = *(const PG8_LAS bf16x8*)(lds + PG8_SA(b, h) + aoff + m * 2048 + k * 1024); } while (0)
; #define PG8_LDB(dst, b, h) do { _Pragma("unroll") for (int n = 0; n < 2; ++n) _Pragma("unroll") for (int k = 0; k < 2; ++k) dst[n][k] = *(const PG8_LAS bf16x8*)(lds + PG8_SB(b, h) + boff + n * 2048 + k * 1024); } while (0)
; #define PG8_MMA(ai, bj, At, Bt) do { __builtin_amdgcn_s_setprio(1); _Pragma("unroll") for (int m = 0; m < 4; ++m) _Pragma("unroll") for (int n = 0; n < 2; ++n) _Pragma("unroll") for (int k = 0; k < 2; ++k) \
;         acc[ai][bj][m][n] = __builtin_amdgcn_mfma_f32_16x16x32_bf16(Bt[n][k], At[m][k], acc[ai][bj][m][n], 0, 0, 0); __builtin_amdgcn_s_setprio(0); } while (0)
; #define PG8_WAIT_V(n) asm volatile("s_waitcnt vmcnt(" #n ")" ::: "memory")
; #define PG8_BAR __builtin_amdgcn_s_barrier()
; template <class Epi, class Sched, bool ALIGN_EPI = false, bool SP2 = false>
; __device__ __forceinline__ void gemm_phase(PG8_LAS unsigned char* lds, const Gemm g, const Sched& S, const Epi& E) {
;     ...
;         for (int t = 0; t < nt; t += 2) {
;             const bool last = (t == nt - 2);
;             const char* a1 = cA + (size_t)(t + 1) * kstep;
;             const char* a2 = last ? nA : cA + (size_t)(t + 2) * kstep; const char* b2 = last ? nB : cB + (size_t)(t + 2) * kstep;
;             const char* a3 = a2 + kstep; const char* b3 = b2 + kstep;
;             if (last && has_next) S.a_ready(nxt);
;             if constexpr (SP2) {
;             PG8_LDB(B0, 0, 0); PG8_LDB(B1, 0, 1); PG8_SCHED; PG8_LDA(At, 0, 0); PG8_STAGE(PG8_SA(1, 1), a1 + hstep, voffA);
;             PG8_WAIT_V(8); PG8_WAIT_L(0); PG8_BAR; PG8_MMA(0, 0, At, B0); PG8_MMA(0, 1, At, B1); PG8_BAR; PG8_SCHED;
;             PG8_LDA(At, 0, 1); PG8_STAGE(PG8_SB(0, 0), b2, voffB); PG8_STAGE(PG8_SB(0, 1), b2 + hstep, voffB); PG8_STAGE(PG8_SA(0, 0), a2, voffA);
;             PG8_WAIT_V(8); PG8_WAIT_L(0); PG8_BAR; PG8_MMA(1, 0, At, B0); PG8_MMA(1, 1, At, B1); PG8_BAR; PG8_SCHED;
.LBB0_530:
	s_add_i32 s21, s17, 2
	s_add_u32 s23, s24, 0xfff00080
	s_addc_u32 s26, s25, -1
	s_add_i32 s30, 0, 0x10000
	s_cmp_eq_u32 s14, s17
	s_cselect_b32 s29, s55, s26
	s_cselect_b32 s28, s54, s23
	s_cselect_b32 s27, s57, s16
	s_cselect_b32 s26, s56, s15
	s_add_i32 s17, 0, 0x14000
	v_add_u32_e32 v142, s30, v190
	v_add_u32_e32 v170, s17, v190
	ds_read_b128 v[130:133], v142
	ds_read_b128 v[134:137], v142 offset:1024
	ds_read_b128 v[138:141], v142 offset:2048
	ds_read_b128 v[142:145], v142 offset:3072
	ds_read_b128 v[146:149], v170
	ds_read_b128 v[150:153], v170 offset:1024
	ds_read_b128 v[178:181], v170 offset:2048
	ds_read_b128 v[182:185], v170 offset:3072
	v_lshl_add_u64 v[170:171], s[24:25], 0, v[176:177]
	s_add_i32 m0, s35, 0xc000
	ds_read_b128 v[186:189], v192
	ds_read_b128 v[194:197], v192 offset:1024
	ds_read_b128 v[198:201], v192 offset:2048
	ds_read_b128 v[202:205], v192 offset:3072
	ds_read_b128 v[206:209], v192 offset:4096
	ds_read_b128 v[220:223], v192 offset:5120
	ds_read_b128 v[224:227], v192 offset:6144
	ds_read_b128 v[228:231], v192 offset:7168
	global_load_lds_dwordx4 v[170:171], off
	v_lshl_add_u64 v[170:171], s[24:25], 0, v[174:175]
	s_add_i32 m0, s35, 0xe000
	s_nop 0
	global_load_lds_dwordx4 v[170:171], off
	s_waitcnt vmcnt(8)
	s_waitcnt lgkmcnt(0)
	s_setprio 3
	s_barrier
	v_mfma_f32_16x16x32_bf16 v[126:129], v[130:133], v[186:189], v[126:129]
	v_mfma_f32_16x16x32_bf16 v[122:125], v[138:141], v[186:189], v[122:125]
	v_mfma_f32_16x16x32_bf16 v[118:121], v[130:133], v[198:201], v[118:121]
	v_mfma_f32_16x16x32_bf16 v[114:117], v[138:141], v[198:201], v[114:117]
	v_mfma_f32_16x16x32_bf16 v[102:105], v[130:133], v[206:209], v[102:105]
	v_mfma_f32_16x16x32_bf16 v[94:97], v[138:141], v[206:209], v[94:97]
	v_mfma_f32_16x16x32_bf16 v[86:89], v[130:133], v[224:227], v[86:89]
	v_mfma_f32_16x16x32_bf16 v[78:81], v[138:141], v[224:227], v[78:81]
	v_mfma_f32_16x16x32_bf16 v[126:129], v[134:137], v[194:197], v[126:129]
	v_mfma_f32_16x16x32_bf16 v[122:125], v[142:145], v[194:197], v[122:125]
	v_mfma_f32_16x16x32_bf16 v[118:121], v[134:137], v[202:205], v[118:121]
	v_mfma_f32_16x16x32_bf16 v[114:117], v[142:145], v[202:205], v[114:117]
	v_mfma_f32_16x16x32_bf16 v[102:105], v[134:137], v[220:223], v[102:105]
	v_mfma_f32_16x16x32_bf16 v[94:97], v[142:145], v[220:223], v[94:97]
	v_mfma_f32_16x16x32_bf16 v[86:89], v[134:137], v[228:231], v[86:89]
	v_mfma_f32_16x16x32_bf16 v[78:81], v[142:145], v[228:231], v[78:81]
	v_mfma_f32_16x16x32_bf16 v[110:113], v[146:149], v[186:189], v[110:113]
	v_mfma_f32_16x16x32_bf16 v[106:109], v[178:181], v[186:189], v[106:109]
	v_mfma_f32_16x16x32_bf16 v[98:101], v[146:149], v[198:201], v[98:101]
	v_mfma_f32_16x16x32_bf16 v[90:93], v[178:181], v[198:201], v[90:93]
	v_mfma_f32_16x16x32_bf16 v[82:85], v[146:149], v[206:209], v[82:85]
	v_mfma_f32_16x16x32_bf16 v[74:77], v[178:181], v[206:209], v[74:77]
	v_mfma_f32_16x16x32_bf16 v[70:73], v[146:149], v[224:227], v[70:73]
	v_mfma_f32_16x16x32_bf16 v[66:69], v[178:181], v[224:227], v[66:69]
	v_mfma_f32_16x16x32_bf16 v[110:113], v[150:153], v[194:197], v[110:113]
	v_mfma_f32_16x16x32_bf16 v[106:109], v[182:185], v[194:197], v[106:109]
	v_mfma_f32_16x16x32_bf16 v[98:101], v[150:153], v[202:205], v[98:101]
	v_mfma_f32_16x16x32_bf16 v[90:93], v[182:185], v[202:205], v[90:93]
	v_mfma_f32_16x16x32_bf16 v[82:85], v[150:153], v[220:223], v[82:85]
	v_mfma_f32_16x16x32_bf16 v[74:77], v[182:185], v[220:223], v[74:77]
	v_mfma_f32_16x16x32_bf16 v[70:73], v[150:153], v[228:231], v[70:73]
	v_mfma_f32_16x16x32_bf16 v[66:69], v[182:185], v[228:231], v[66:69]
	s_barrier
	s_setprio 0
	s_add_i32 s23, s30, s34
	v_lshl_add_u64 v[170:171], s[26:27], 0, v[158:159]
	s_mov_b32 m0, s23
	ds_read_b128 v[186:189], v192 offset:16384
	ds_read_b128 v[194:197], v192 offset:17408
	ds_read_b128 v[198:201], v192 offset:18432
	ds_read_b128 v[202:205], v192 offset:19456
	ds_read_b128 v[206:209], v192 offset:20480
	ds_read_b128 v[220:223], v192 offset:21504
	ds_read_b128 v[224:227], v192 offset:22528
	ds_read_b128 v[228:231], v192 offset:23552
	global_load_lds_dwordx4 v[170:171], off
	s_add_i32 m0, s23, 0x2000
	s_add_u32 s58, s26, 0x100000
	v_lshl_add_u64 v[210:211], s[26:27], 0, v[172:173]
	s_addc_u32 s59, s27, 0
	s_add_i32 s17, s17, s34
	global_load_lds_dwordx4 v[210:211], off
	v_lshl_add_u64 v[232:233], s[58:59], 0, v[158:159]
	s_mov_b32 m0, s17
	v_lshl_add_u64 v[234:235], s[28:29], 0, v[156:157]
	global_load_lds_dwordx4 v[232:233], off
	v_lshl_add_u64 v[232:233], s[58:59], 0, v[172:173]
	s_add_i32 m0, s17, 0x2000
	s_nop 0
	global_load_lds_dwordx4 v[232:233], off
	v_lshl_add_u64 v[232:233], s[28:29], 0, v[154:155]
	s_mov_b32 m0, s35
	s_nop 0
	global_load_lds_dwordx4 v[232:233], off
	s_mov_b32 m0, s4
	s_nop 0
	global_load_lds_dwordx4 v[234:235], off
	s_waitcnt vmcnt(8)
	s_waitcnt lgkmcnt(0)
	s_setprio 3
	s_barrier
; #define PG8_STAGE(bufoff, gbase, voff) do { _Pragma("unroll") for (int _i = 0; _i < 2; ++_i) \
;         __builtin_amdgcn_global_load_lds((const unsigned*)((const char*)(gbase) + (voff)[_i]), (PG8_LAS unsigned*)(lds + (bufoff) + ldsw + _i * 8192), 16, 0, 0); } while (0)
; #define PG8_LDA(dst, b, h) do { _Pragma("unroll") for (int m = 0; m < 4; ++m) _Pragma("unroll") for (int k = 0; k < 2; ++k) dst[m][k] = *(const PG8_LAS bf16x8*)(lds + PG8_SA(b, h) + aoff + m * 2048 + k * 1024); } while (0)
; #define PG8_LDB(dst, b, h) do { _Pragma("unroll") for (int n = 0; n < 2; ++n) _Pragma("unroll") for (int k = 0; k < 2; ++k) dst[n][k] = *(const PG8_LAS bf16x8*)(lds + PG8_SB(b, h) + boff + n * 2048 + k * 1024); } while (0)
; #define PG8_MMA(ai, bj, At, Bt) do { __builtin_amdgcn_s_setprio(1); _Pragma("unroll") for (int m = 0; m < 4; ++m) _Pragma("unroll") for (int n = 0; n < 2; ++n) _Pragma("unroll") for (int k = 0; k < 2; ++k) \
;         acc[ai][bj][m][n] = __builtin_amdgcn_mfma_f32_16x16x32_bf16(Bt[n][k], At[m][k], acc[ai][bj][m][n], 0, 0, 0); __builtin_amdgcn_s_setprio(0); } while (0)
; #define PG8_WAIT_V(n) asm volatile("s_waitcnt vmcnt(" #n ")" ::: "memory")
; #define PG8_WAIT_L(n) asm volatile("s_waitcnt lgkmcnt(" #n ")" ::: "memory")
; #define PG8_BAR __builtin_amdgcn_s_barrier()
; #define PG8_SCHED __builtin_amdgcn_sched_barrier(0)
; template <class Epi, class Sched, bool ALIGN_EPI = false, bool SP2 = false>
; __device__ __forceinline__ void gemm_phase(PG8_LAS unsigned char* lds, const Gemm g, const Sched& S, const Epi& E) {
;     ...
;             PG8_WAIT_V(8); PG8_WAIT_L(0); PG8_BAR; PG8_MMA(1, 0, At, B0); PG8_MMA(1, 1, At, B1); PG8_BAR; PG8_SCHED;
;             PG8_LDB(B0, 1, 0); PG8_LDB(B1, 1, 1); PG8_SCHED; PG8_LDA(At, 1, 0); PG8_STAGE(PG8_SA(0, 1), a2 + hstep, voffA);
;             PG8_WAIT_V(8); PG8_WAIT_L(0); PG8_BAR; PG8_MMA(0, 0, At, B0); PG8_MMA(0, 1, At, B1); PG8_BAR; PG8_SCHED;
	v_mfma_f32_16x16x32_bf16 v[62:65], v[130:133], v[186:189], v[62:65]
	v_mfma_f32_16x16x32_bf16 v[58:61], v[138:141], v[186:189], v[58:61]
	v_mfma_f32_16x16x32_bf16 v[54:57], v[130:133], v[198:201], v[54:57]
	v_mfma_f32_16x16x32_bf16 v[46:49], v[138:141], v[198:201], v[46:49]
	v_mfma_f32_16x16x32_bf16 v[38:41], v[130:133], v[206:209], v[38:41]
	v_mfma_f32_16x16x32_bf16 v[30:33], v[138:141], v[206:209], v[30:33]
	v_mfma_f32_16x16x32_bf16 v[22:25], v[130:133], v[224:227], v[22:25]
	v_mfma_f32_16x16x32_bf16 v[14:17], v[138:141], v[224:227], v[14:17]
	v_mfma_f32_16x16x32_bf16 v[62:65], v[134:137], v[194:197], v[62:65]
	v_mfma_f32_16x16x32_bf16 v[58:61], v[142:145], v[194:197], v[58:61]
	v_mfma_f32_16x16x32_bf16 v[54:57], v[134:137], v[202:205], v[54:57]
	v_mfma_f32_16x16x32_bf16 v[46:49], v[142:145], v[202:205], v[46:49]
	v_mfma_f32_16x16x32_bf16 v[38:41], v[134:137], v[220:223], v[38:41]
	v_mfma_f32_16x16x32_bf16 v[30:33], v[142:145], v[220:223], v[30:33]
	v_mfma_f32_16x16x32_bf16 v[22:25], v[134:137], v[228:231], v[22:25]
	v_mfma_f32_16x16x32_bf16 v[14:17], v[142:145], v[228:231], v[14:17]
	v_mfma_f32_16x16x32_bf16 v[50:53], v[146:149], v[186:189], v[50:53]
	v_mfma_f32_16x16x32_bf16 v[42:45], v[178:181], v[186:189], v[42:45]
	v_mfma_f32_16x16x32_bf16 v[34:37], v[146:149], v[198:201], v[34:37]
	v_mfma_f32_16x16x32_bf16 v[26:29], v[178:181], v[198:201], v[26:29]
	v_mfma_f32_16x16x32_bf16 v[18:21], v[146:149], v[206:209], v[18:21]
	v_mfma_f32_16x16x32_bf16 v[10:13], v[178:181], v[206:209], v[10:13]
	v_mfma_f32_16x16x32_bf16 v[6:9], v[146:149], v[224:227], v[6:9]
	v_mfma_f32_16x16x32_bf16 v[2:5], v[178:181], v[224:227], v[2:5]
	v_mfma_f32_16x16x32_bf16 v[50:53], v[150:153], v[194:197], v[50:53]
	v_mfma_f32_16x16x32_bf16 v[42:45], v[182:185], v[194:197], v[42:45]
	v_mfma_f32_16x16x32_bf16 v[34:37], v[150:153], v[202:205], v[34:37]
	v_mfma_f32_16x16x32_bf16 v[26:29], v[182:185], v[202:205], v[26:29]
	v_mfma_f32_16x16x32_bf16 v[18:21], v[150:153], v[220:223], v[18:21]
	v_mfma_f32_16x16x32_bf16 v[10:13], v[182:185], v[220:223], v[10:13]
	v_mfma_f32_16x16x32_bf16 v[6:9], v[150:153], v[228:231], v[6:9]
	v_mfma_f32_16x16x32_bf16 v[2:5], v[182:185], v[228:231], v[2:5]
	s_barrier
	s_setprio 0
	s_add_i32 s17, 0, 0x18000
	s_add_i32 s23, 0, 0x1c000
	v_add_u32_e32 v142, s17, v190
	v_add_u32_e32 v182, s23, v190
	ds_read_b128 v[130:133], v142
	ds_read_b128 v[134:137], v142 offset:1024
	ds_read_b128 v[138:141], v142 offset:2048
	ds_read_b128 v[142:145], v142 offset:3072
	ds_read_b128 v[146:149], v182
	ds_read_b128 v[150:153], v182 offset:1024
	ds_read_b128 v[178:181], v182 offset:2048
	ds_read_b128 v[182:185], v182 offset:3072
	s_add_u32 s28, s28, 0x100000
	s_addc_u32 s29, s29, 0
	s_mov_b32 m0, s5
	v_lshl_add_u64 v[236:237], s[28:29], 0, v[154:155]
	ds_read_b128 v[186:189], v192 offset:32768
	ds_read_b128 v[194:197], v192 offset:33792
	ds_read_b128 v[198:201], v192 offset:34816
	ds_read_b128 v[202:205], v192 offset:35840
	ds_read_b128 v[206:209], v192 offset:36864
	ds_read_b128 v[220:223], v192 offset:37888
	ds_read_b128 v[224:227], v192 offset:38912
	ds_read_b128 v[228:231], v192 offset:39936
	global_load_lds_dwordx4 v[236:237], off
	v_lshl_add_u64 v[236:237], s[28:29], 0, v[156:157]
	s_mov_b32 m0, s6
	s_nop 0
	global_load_lds_dwordx4 v[236:237], off
	s_waitcnt vmcnt(8)
	s_waitcnt lgkmcnt(0)
	s_setprio 3
	s_barrier
	v_mfma_f32_16x16x32_bf16 v[126:129], v[130:133], v[186:189], v[126:129]
	v_mfma_f32_16x16x32_bf16 v[122:125], v[138:141], v[186:189], v[122:125]
	v_mfma_f32_16x16x32_bf16 v[118:121], v[130:133], v[198:201], v[118:121]
	v_mfma_f32_16x16x32_bf16 v[114:117], v[138:141], v[198:201], v[114:117]
	v_mfma_f32_16x16x32_bf16 v[102:105], v[130:133], v[206:209], v[102:105]
	v_mfma_f32_16x16x32_bf16 v[94:97], v[138:141], v[206:209], v[94:97]
	v_mfma_f32_16x16x32_bf16 v[86:89], v[130:133], v[224:227], v[86:89]
	v_mfma_f32_16x16x32_bf16 v[78:81], v[138:141], v[224:227], v[78:81]
	v_mfma_f32_16x16x32_bf16 v[126:129], v[134:137], v[194:197], v[126:129]
	v_mfma_f32_16x16x32_bf16 v[122:125], v[142:145], v[194:197], v[122:125]
	v_mfma_f32_16x16x32_bf16 v[118:121], v[134:137], v[202:205], v[118:121]
	v_mfma_f32_16x16x32_bf16 v[114:117], v[142:145], v[202:205], v[114:117]
	v_mfma_f32_16x16x32_bf16 v[102:105], v[134:137], v[220:223], v[102:105]
	v_mfma_f32_16x16x32_bf16 v[94:97], v[142:145], v[220:223], v[94:97]
	v_mfma_f32_16x16x32_bf16 v[86:89], v[134:137], v[228:231], v[86:89]
	v_mfma_f32_16x16x32_bf16 v[78:81], v[142:145], v[228:231], v[78:81]
	v_mfma_f32_16x16x32_bf16 v[110:113], v[146:149], v[186:189], v[110:113]
	v_mfma_f32_16x16x32_bf16 v[106:109], v[178:181], v[186:189], v[106:109]
	v_mfma_f32_16x16x32_bf16 v[98:101], v[146:149], v[198:201], v[98:101]
	v_mfma_f32_16x16x32_bf16 v[90:93], v[178:181], v[198:201], v[90:93]
	v_mfma_f32_16x16x32_bf16 v[82:85], v[146:149], v[206:209], v[82:85]
	v_mfma_f32_16x16x32_bf16 v[74:77], v[178:181], v[206:209], v[74:77]
	v_mfma_f32_16x16x32_bf16 v[70:73], v[146:149], v[224:227], v[70:73]
	v_mfma_f32_16x16x32_bf16 v[66:69], v[178:181], v[224:227], v[66:69]
	v_mfma_f32_16x16x32_bf16 v[110:113], v[150:153], v[194:197], v[110:113]
	v_mfma_f32_16x16x32_bf16 v[106:109], v[182:185], v[194:197], v[106:109]
	v_mfma_f32_16x16x32_bf16 v[98:101], v[150:153], v[202:205], v[98:101]
	v_mfma_f32_16x16x32_bf16 v[90:93], v[182:185], v[202:205], v[90:93]
	v_mfma_f32_16x16x32_bf16 v[82:85], v[150:153], v[220:223], v[82:85]
	v_mfma_f32_16x16x32_bf16 v[74:77], v[182:185], v[220:223], v[74:77]
	v_mfma_f32_16x16x32_bf16 v[70:73], v[150:153], v[228:231], v[70:73]
	v_mfma_f32_16x16x32_bf16 v[66:69], v[182:185], v[228:231], v[66:69]
	s_barrier
; #define PG8_STAGE(bufoff, gbase, voff) do { _Pragma("unroll") for (int _i = 0; _i < 2; ++_i) \
;         __builtin_amdgcn_global_load_lds((const unsigned*)((const char*)(gbase) + (voff)[_i]), (PG8_LAS unsigned*)(lds + (bufoff) + ldsw + _i * 8192), 16, 0, 0); } while (0)
; #define PG8_LDA(dst, b, h) do { _Pragma("unroll") for (int m = 0; m < 4; ++m) _Pragma("unroll") for (int k = 0; k < 2; ++k) dst[m][k] = *(const PG8_LAS bf16x8*)(lds + PG8_SA(b, h) + aoff + m * 2048 + k * 1024); } while (0)
; #define PG8_MMA(ai, bj, At, Bt) do { __builtin_amdgcn_s_setprio(1); _Pragma("unroll") for (int m = 0; m < 4; ++m) _Pragma("unroll") for (int n = 0; n < 2; ++n) _Pragma("unroll") for (int k = 0; k < 2; ++k) \
;         acc[ai][bj][m][n] = __builtin_amdgcn_mfma_f32_16x16x32_bf16(Bt[n][k], At[m][k], acc[ai][bj][m][n], 0, 0, 0); __builtin_amdgcn_s_setprio(0); } while (0)
; #define PG8_WAIT_V(n) asm volatile("s_waitcnt vmcnt(" #n ")" ::: "memory")
; #define PG8_WAIT_L(n) asm volatile("s_waitcnt lgkmcnt(" #n ")" ::: "memory")
; #define PG8_BAR __builtin_amdgcn_s_barrier()
; #define PG8_SCHED __builtin_amdgcn_sched_barrier(0)
; template <class Epi, class Sched, bool ALIGN_EPI = false, bool SP2 = false>
; __device__ __forceinline__ void gemm_phase(PG8_LAS unsigned char* lds, const Gemm g, const Sched& S, const Epi& E) {
;     ...
;             PG8_WAIT_V(8); PG8_WAIT_L(0); PG8_BAR; PG8_MMA(0, 0, At, B0); PG8_MMA(0, 1, At, B1); PG8_BAR; PG8_SCHED;
;             PG8_LDA(At, 1, 1); PG8_STAGE(PG8_SB(1, 0), b3, voffB); PG8_STAGE(PG8_SB(1, 1), b3 + hstep, voffB); PG8_STAGE(PG8_SA(1, 0), a3, voffA);
;             PG8_WAIT_V(8); PG8_WAIT_L(0); PG8_BAR; PG8_MMA(1, 0, At, B0); PG8_MMA(1, 1, At, B1); PG8_BAR; PG8_SCHED;
	s_setprio 0
	s_add_i32 s17, s17, s34
	v_lshl_add_u64 v[170:171], v[170:171], 0, s[96:97]
	s_mov_b32 m0, s17
	ds_read_b128 v[186:189], v192 offset:49152
	ds_read_b128 v[194:197], v192 offset:50176
	ds_read_b128 v[198:201], v192 offset:51200
	ds_read_b128 v[202:205], v192 offset:52224
	ds_read_b128 v[206:209], v192 offset:53248
	ds_read_b128 v[220:223], v192 offset:54272
	ds_read_b128 v[224:227], v192 offset:55296
	ds_read_b128 v[228:231], v192 offset:56320
	global_load_lds_dwordx4 v[170:171], off
	s_add_i32 m0, s17, 0x2000
	s_add_u32 s26, s26, 0x100080
	v_lshl_add_u64 v[170:171], v[210:211], 0, s[96:97]
	s_addc_u32 s27, s27, 0
	s_add_i32 s17, s23, s34
	global_load_lds_dwordx4 v[170:171], off
	v_lshl_add_u64 v[170:171], s[26:27], 0, v[158:159]
	s_mov_b32 m0, s17
	s_nop 0
	global_load_lds_dwordx4 v[170:171], off
	v_lshl_add_u64 v[170:171], s[26:27], 0, v[172:173]
	s_add_i32 m0, s17, 0x2000
	s_nop 0
	global_load_lds_dwordx4 v[170:171], off
	v_lshl_add_u64 v[170:171], v[232:233], 0, s[96:97]
	s_mov_b32 m0, s9
	s_nop 0
	global_load_lds_dwordx4 v[170:171], off
	v_lshl_add_u64 v[170:171], v[234:235], 0, s[96:97]
	s_mov_b32 m0, s10
	s_nop 0
	global_load_lds_dwordx4 v[170:171], off
	s_waitcnt vmcnt(8)
	s_waitcnt lgkmcnt(0)
	s_setprio 3
	s_barrier
	v_mfma_f32_16x16x32_bf16 v[62:65], v[130:133], v[186:189], v[62:65]
	v_mfma_f32_16x16x32_bf16 v[58:61], v[138:141], v[186:189], v[58:61]
	v_mfma_f32_16x16x32_bf16 v[54:57], v[130:133], v[198:201], v[54:57]
	v_mfma_f32_16x16x32_bf16 v[46:49], v[138:141], v[198:201], v[46:49]
	v_mfma_f32_16x16x32_bf16 v[38:41], v[130:133], v[206:209], v[38:41]
	v_mfma_f32_16x16x32_bf16 v[30:33], v[138:141], v[206:209], v[30:33]
	v_mfma_f32_16x16x32_bf16 v[22:25], v[130:133], v[224:227], v[22:25]
	v_mfma_f32_16x16x32_bf16 v[14:17], v[138:141], v[224:227], v[14:17]
	v_mfma_f32_16x16x32_bf16 v[62:65], v[134:137], v[194:197], v[62:65]
	v_mfma_f32_16x16x32_bf16 v[58:61], v[142:145], v[194:197], v[58:61]
	v_mfma_f32_16x16x32_bf16 v[54:57], v[134:137], v[202:205], v[54:57]
	v_mfma_f32_16x16x32_bf16 v[46:49], v[142:145], v[202:205], v[46:49]
	v_mfma_f32_16x16x32_bf16 v[38:41], v[134:137], v[220:223], v[38:41]
	v_mfma_f32_16x16x32_bf16 v[30:33], v[142:145], v[220:223], v[30:33]
	v_mfma_f32_16x16x32_bf16 v[22:25], v[134:137], v[228:231], v[22:25]
	v_mfma_f32_16x16x32_bf16 v[14:17], v[142:145], v[228:231], v[14:17]
	v_mfma_f32_16x16x32_bf16 v[50:53], v[146:149], v[186:189], v[50:53]
	v_mfma_f32_16x16x32_bf16 v[42:45], v[178:181], v[186:189], v[42:45]
	v_mfma_f32_16x16x32_bf16 v[34:37], v[146:149], v[198:201], v[34:37]
	v_mfma_f32_16x16x32_bf16 v[26:29], v[178:181], v[198:201], v[26:29]
	v_mfma_f32_16x16x32_bf16 v[18:21], v[146:149], v[206:209], v[18:21]
	v_mfma_f32_16x16x32_bf16 v[10:13], v[178:181], v[206:209], v[10:13]
	v_mfma_f32_16x16x32_bf16 v[6:9], v[146:149], v[224:227], v[6:9]
	v_mfma_f32_16x16x32_bf16 v[2:5], v[178:181], v[224:227], v[2:5]
	v_mfma_f32_16x16x32_bf16 v[50:53], v[150:153], v[194:197], v[50:53]
	v_mfma_f32_16x16x32_bf16 v[42:45], v[182:185], v[194:197], v[42:45]
	v_mfma_f32_16x16x32_bf16 v[34:37], v[150:153], v[202:205], v[34:37]
	v_mfma_f32_16x16x32_bf16 v[26:29], v[182:185], v[202:205], v[26:29]
	v_mfma_f32_16x16x32_bf16 v[18:21], v[150:153], v[220:223], v[18:21]
	v_mfma_f32_16x16x32_bf16 v[10:13], v[182:185], v[220:223], v[10:13]
	v_mfma_f32_16x16x32_bf16 v[6:9], v[150:153], v[228:231], v[6:9]
	v_mfma_f32_16x16x32_bf16 v[2:5], v[182:185], v[228:231], v[2:5]
	s_barrier
	s_setprio 0
	s_add_u32 s15, s15, 0x100
	s_addc_u32 s16, s16, 0
	s_add_u32 s24, s24, 0x100
	s_addc_u32 s25, s25, 0
	s_cmp_ge_i32 s21, s13
	s_mov_b32 s17, s21
	s_cbranch_scc0 .LBB0_530
	s_and_b64 vcc, exec, s[46:47]
	s_cbranch_vccz .LBB0_533
	s_barrier

; #define PG8_STAGE(bufoff, gbase, voff) do { _Pragma("unroll") for (int _i = 0; _i < 2; ++_i) \
;         __builtin_amdgcn_global_load_lds((const unsigned*)((const char*)(gbase) + (voff)[_i]), (PG8_LAS unsigned*)(lds + (bufoff) + ldsw + _i * 8192), 16, 0, 0); } while (0)
; #define PG8_LDA(dst, b, h) do { _Pragma("unroll") for (int m = 0; m < 4; ++m) _Pragma("unroll") for (int k = 0; k < 2; ++k) dst[m][k] = *(const PG8_LAS bf16x8*)(lds + PG8_SA(b, h) + aoff + m * 2048 + k * 1024); } while (0)
; #define PG8_LDB(dst, b, h) do { _Pragma("unroll") for (int n = 0; n < 2; ++n) _Pragma("unroll") for (int k = 0; k < 2; ++k) dst[n][k] = *(const PG8_LAS bf16x8*)(lds + PG8_SB(b, h) + boff + n * 2048 + k * 1024); } while (0)
; #define PG8_MMA(ai, bj, At, Bt) do { __builtin_amdgcn_s_setprio(1); _Pragma("unroll") for (int m = 0; m < 4; ++m) _Pragma("unroll") for (int n = 0; n < 2; ++n) _Pragma("unroll") for (int k = 0; k < 2; ++k) \
;         acc[ai][bj][m][n] = __builtin_amdgcn_mfma_f32_16x16x32_bf16(Bt[n][k], At[m][k], acc[ai][bj][m][n], 0, 0, 0); __builtin_amdgcn_s_setprio(0); } while (0)
; #define PG8_WAIT_V(n) asm volatile("s_waitcnt vmcnt(" #n ")" ::: "memory")
; #define PG8_BAR __builtin_amdgcn_s_barrier()
; template <class Epi, class Sched, bool ALIGN_EPI = false, bool SP2 = false>
; __device__ __forceinline__ void gemm_phase(PG8_LAS unsigned char* lds, const Gemm g, const Sched& S, const Epi& E) {
;     ...
;         for (int t = 0; t < nt; t += 2) {
;             const bool last = (t == nt - 2);
;             const char* a1 = cA + (size_t)(t + 1) * kstep;
;             const char* a2 = last ? nA : cA + (size_t)(t + 2) * kstep; const char* b2 = last ? nB : cB + (size_t)(t + 2) * kstep;
;             const char* a3 = a2 + kstep; const char* b3 = b2 + kstep;
;             if (last && has_next) S.a_ready(nxt);
;             if constexpr (SP2) {
;             PG8_LDB(B0, 0, 0); PG8_LDB(B1, 0, 1); PG8_SCHED; PG8_LDA(At, 0, 0); PG8_STAGE(PG8_SA(1, 1), a1 + hstep, voffA);
;             PG8_WAIT_V(8); PG8_WAIT_L(0); PG8_BAR; PG8_MMA(0, 0, At, B0); PG8_MMA(0, 1, At, B1); PG8_BAR; PG8_SCHED;
;             PG8_LDA(At, 0, 1); PG8_STAGE(PG8_SB(0, 0), b2, voffB); PG8_STAGE(PG8_SB(0, 1), b2 + hstep, voffB); PG8_STAGE(PG8_SA(0, 0), a2, voffA);
;             PG8_WAIT_V(8); PG8_WAIT_L(0); PG8_BAR; PG8_MMA(1, 0, At, B0); PG8_MMA(1, 1, At, B1); PG8_BAR; PG8_SCHED;
.LBB0_710:
	s_add_u32 s22, vcc_lo, 0xfff00080
	s_addc_u32 s23, vcc_hi, -1
	s_add_i32 s68, 0, 0x10000
	s_cmp_eq_u32 s65, 60
	s_cselect_b32 s25, s30, s23
	s_cselect_b32 s24, s31, s22
	s_cselect_b32 s23, s61, s17
	s_cselect_b32 s22, s63, s16
	s_add_i32 s70, 0, 0x14000
	v_add_u32_e32 v70, s68, v220
	v_add_u32_e32 v170, s70, v220
	ds_read_b128 v[50:53], v70
	ds_read_b128 v[54:57], v70 offset:1024
	ds_read_b128 v[66:69], v70 offset:2048
	ds_read_b128 v[70:73], v70 offset:3072
	ds_read_b128 v[74:77], v170
	ds_read_b128 v[86:89], v170 offset:1024
	ds_read_b128 v[154:157], v170 offset:2048
	ds_read_b128 v[188:191], v170 offset:3072
	v_lshl_add_u64 v[170:171], vcc, 0, v[186:187]
	s_add_i32 m0, s10, 0xc000
	ds_read_b128 v[192:195], v222
	ds_read_b128 v[196:199], v222 offset:1024
	ds_read_b128 v[200:203], v222 offset:2048
	ds_read_b128 v[204:207], v222 offset:3072
	ds_read_b128 v[224:227], v222 offset:4096
	ds_read_b128 v[228:231], v222 offset:5120
	ds_read_b128 v[232:235], v222 offset:6144
	ds_read_b128 v[236:239], v222 offset:7168
	global_load_lds_dwordx4 v[170:171], off
	v_lshl_add_u64 v[170:171], vcc, 0, v[184:185]
	s_add_i32 m0, s10, 0xe000
	s_nop 0
	global_load_lds_dwordx4 v[170:171], off
	s_waitcnt vmcnt(8)
	s_waitcnt lgkmcnt(0)
	s_setprio 3
	s_barrier
	v_mfma_f32_16x16x32_bf16 v[142:145], v[50:53], v[192:195], v[142:145]
	v_mfma_f32_16x16x32_bf16 v[130:133], v[66:69], v[192:195], v[130:133]
	v_mfma_f32_16x16x32_bf16 v[138:141], v[50:53], v[200:203], v[138:141]
	v_mfma_f32_16x16x32_bf16 v[126:129], v[66:69], v[200:203], v[126:129]
	v_mfma_f32_16x16x32_bf16 v[118:121], v[50:53], v[224:227], v[118:121]
	v_mfma_f32_16x16x32_bf16 v[110:113], v[66:69], v[224:227], v[110:113]
	v_mfma_f32_16x16x32_bf16 v[98:101], v[50:53], v[232:235], v[98:101]
	v_mfma_f32_16x16x32_bf16 v[94:97], v[66:69], v[232:235], v[94:97]
	v_mfma_f32_16x16x32_bf16 v[142:145], v[54:57], v[196:199], v[142:145]
	v_mfma_f32_16x16x32_bf16 v[130:133], v[70:73], v[196:199], v[130:133]
	v_mfma_f32_16x16x32_bf16 v[138:141], v[54:57], v[204:207], v[138:141]
	v_mfma_f32_16x16x32_bf16 v[126:129], v[70:73], v[204:207], v[126:129]
	v_mfma_f32_16x16x32_bf16 v[118:121], v[54:57], v[228:231], v[118:121]
	v_mfma_f32_16x16x32_bf16 v[110:113], v[70:73], v[228:231], v[110:113]
	v_mfma_f32_16x16x32_bf16 v[98:101], v[54:57], v[236:239], v[98:101]
	v_mfma_f32_16x16x32_bf16 v[94:97], v[70:73], v[236:239], v[94:97]
	v_mfma_f32_16x16x32_bf16 v[150:153], v[74:77], v[192:195], v[150:153]
	v_mfma_f32_16x16x32_bf16 v[146:149], v[154:157], v[192:195], v[146:149]
	v_mfma_f32_16x16x32_bf16 v[134:137], v[74:77], v[200:203], v[134:137]
	v_mfma_f32_16x16x32_bf16 v[122:125], v[154:157], v[200:203], v[122:125]
	v_mfma_f32_16x16x32_bf16 v[114:117], v[74:77], v[224:227], v[114:117]
	v_mfma_f32_16x16x32_bf16 v[106:109], v[154:157], v[224:227], v[106:109]
	v_mfma_f32_16x16x32_bf16 v[102:105], v[74:77], v[232:235], v[102:105]
	v_mfma_f32_16x16x32_bf16 v[90:93], v[154:157], v[232:235], v[90:93]
	v_mfma_f32_16x16x32_bf16 v[150:153], v[86:89], v[196:199], v[150:153]
	v_mfma_f32_16x16x32_bf16 v[146:149], v[188:191], v[196:199], v[146:149]
	v_mfma_f32_16x16x32_bf16 v[134:137], v[86:89], v[204:207], v[134:137]
	v_mfma_f32_16x16x32_bf16 v[122:125], v[188:191], v[204:207], v[122:125]
	v_mfma_f32_16x16x32_bf16 v[114:117], v[86:89], v[228:231], v[114:117]
	v_mfma_f32_16x16x32_bf16 v[106:109], v[188:191], v[228:231], v[106:109]
	v_mfma_f32_16x16x32_bf16 v[102:105], v[86:89], v[236:239], v[102:105]
	v_mfma_f32_16x16x32_bf16 v[90:93], v[188:191], v[236:239], v[90:93]
	s_barrier
	s_setprio 0
	s_add_i32 s68, s68, s9
	v_lshl_add_u64 v[170:171], s[22:23], 0, v[158:159]
	s_mov_b32 m0, s68
	ds_read_b128 v[192:195], v222 offset:16384
	ds_read_b128 v[196:199], v222 offset:17408
	ds_read_b128 v[200:203], v222 offset:18432
	ds_read_b128 v[204:207], v222 offset:19456
	ds_read_b128 v[224:227], v222 offset:20480
	ds_read_b128 v[228:231], v222 offset:21504
	ds_read_b128 v[232:235], v222 offset:22528
	ds_read_b128 v[236:239], v222 offset:23552
	global_load_lds_dwordx4 v[170:171], off
	s_add_i32 m0, s68, 0x2000
	s_add_u32 s68, s22, 0x100000
	v_lshl_add_u64 v[208:209], s[22:23], 0, v[172:173]
	s_addc_u32 s69, s23, 0
	s_add_i32 s70, s70, s9
	global_load_lds_dwordx4 v[208:209], off
	v_lshl_add_u64 v[210:211], s[68:69], 0, v[158:159]
	s_mov_b32 m0, s70
	v_lshl_add_u64 v[244:245], s[24:25], 0, v[174:175]
	global_load_lds_dwordx4 v[210:211], off
	v_lshl_add_u64 v[210:211], s[68:69], 0, v[172:173]
	s_add_i32 m0, s70, 0x2000
	s_nop 0
	global_load_lds_dwordx4 v[210:211], off
	v_lshl_add_u64 v[210:211], s[24:25], 0, v[176:177]
	s_mov_b32 m0, s10
	s_nop 0
	global_load_lds_dwordx4 v[210:211], off
	s_mov_b32 m0, s11
	s_nop 0
	global_load_lds_dwordx4 v[244:245], off
	s_waitcnt vmcnt(8)
	s_waitcnt lgkmcnt(0)
	s_setprio 3
	s_barrier
; #define PG8_STAGE(bufoff, gbase, voff) do { _Pragma("unroll") for (int _i = 0; _i < 2; ++_i) \
;         __builtin_amdgcn_global_load_lds((const unsigned*)((const char*)(gbase) + (voff)[_i]), (PG8_LAS unsigned*)(lds + (bufoff) + ldsw + _i * 8192), 16, 0, 0); } while (0)
; #define PG8_LDA(dst, b, h) do { _Pragma("unroll") for (int m = 0; m < 4; ++m) _Pragma("unroll") for (int k = 0; k < 2; ++k) dst[m][k] = *(const PG8_LAS bf16x8*)(lds + PG8_SA(b, h) + aoff + m * 2048 + k * 1024); } while (0)
; #define PG8_LDB(dst, b, h) do { _Pragma("unroll") for (int n = 0; n < 2; ++n) _Pragma("unroll") for (int k = 0; k < 2; ++k) dst[n][k] = *(const PG8_LAS bf16x8*)(lds + PG8_SB(b, h) + boff + n * 2048 + k * 1024); } while (0)
; #define PG8_MMA(ai, bj, At, Bt) do { __builtin_amdgcn_s_setprio(1); _Pragma("unroll") for (int m = 0; m < 4; ++m) _Pragma("unroll") for (int n = 0; n < 2; ++n) _Pragma("unroll") for (int k = 0; k < 2; ++k) \
;         acc[ai][bj][m][n] = __builtin_amdgcn_mfma_f32_16x16x32_bf16(Bt[n][k], At[m][k], acc[ai][bj][m][n], 0, 0, 0); __builtin_amdgcn_s_setprio(0); } while (0)
; #define PG8_WAIT_V(n) asm volatile("s_waitcnt vmcnt(" #n ")" ::: "memory")
; #define PG8_WAIT_L(n) asm volatile("s_waitcnt lgkmcnt(" #n ")" ::: "memory")
; #define PG8_BAR __builtin_amdgcn_s_barrier()
; #define PG8_SCHED __builtin_amdgcn_sched_barrier(0)
; template <class Epi, class Sched, bool ALIGN_EPI = false, bool SP2 = false>
; __device__ __forceinline__ void gemm_phase(PG8_LAS unsigned char* lds, const Gemm g, const Sched& S, const Epi& E) {
;     ...
;             PG8_WAIT_V(8); PG8_WAIT_L(0); PG8_BAR; PG8_MMA(1, 0, At, B0); PG8_MMA(1, 1, At, B1); PG8_BAR; PG8_SCHED;
;             PG8_LDB(B0, 1, 0); PG8_LDB(B1, 1, 1); PG8_SCHED; PG8_LDA(At, 1, 0); PG8_STAGE(PG8_SA(0, 1), a2 + hstep, voffA);
;             PG8_WAIT_V(8); PG8_WAIT_L(0); PG8_BAR; PG8_MMA(0, 0, At, B0); PG8_MMA(0, 1, At, B1); PG8_BAR; PG8_SCHED;
	v_mfma_f32_16x16x32_bf16 v[62:65], v[50:53], v[192:195], v[62:65]
	v_mfma_f32_16x16x32_bf16 v[42:45], v[66:69], v[192:195], v[42:45]
	v_mfma_f32_16x16x32_bf16 v[58:61], v[50:53], v[200:203], v[58:61]
	v_mfma_f32_16x16x32_bf16 v[38:41], v[66:69], v[200:203], v[38:41]
	v_mfma_f32_16x16x32_bf16 v[30:33], v[50:53], v[224:227], v[30:33]
	v_mfma_f32_16x16x32_bf16 v[22:25], v[66:69], v[224:227], v[22:25]
	v_mfma_f32_16x16x32_bf16 v[10:13], v[50:53], v[232:235], v[10:13]
	v_mfma_f32_16x16x32_bf16 v[6:9], v[66:69], v[232:235], v[6:9]
	v_mfma_f32_16x16x32_bf16 v[62:65], v[54:57], v[196:199], v[62:65]
	v_mfma_f32_16x16x32_bf16 v[42:45], v[70:73], v[196:199], v[42:45]
	v_mfma_f32_16x16x32_bf16 v[58:61], v[54:57], v[204:207], v[58:61]
	v_mfma_f32_16x16x32_bf16 v[38:41], v[70:73], v[204:207], v[38:41]
	v_mfma_f32_16x16x32_bf16 v[30:33], v[54:57], v[228:231], v[30:33]
	v_mfma_f32_16x16x32_bf16 v[22:25], v[70:73], v[228:231], v[22:25]
	v_mfma_f32_16x16x32_bf16 v[10:13], v[54:57], v[236:239], v[10:13]
	v_mfma_f32_16x16x32_bf16 v[6:9], v[70:73], v[236:239], v[6:9]
	v_mfma_f32_16x16x32_bf16 v[46:49], v[74:77], v[200:203], v[46:49]
	v_mfma_f32_16x16x32_bf16 v[34:37], v[154:157], v[200:203], v[34:37]
	v_mfma_f32_16x16x32_bf16 v[26:29], v[74:77], v[224:227], v[26:29]
	v_mfma_f32_16x16x32_bf16 v[18:21], v[154:157], v[224:227], v[18:21]
	v_mfma_f32_16x16x32_bf16 v[14:17], v[74:77], v[232:235], v[14:17]
	v_mfma_f32_16x16x32_bf16 v[2:5], v[154:157], v[232:235], v[2:5]
	v_mfma_f32_16x16x32_bf16 v[50:53], v[74:77], v[192:195], v[82:85]
	v_mfma_f32_16x16x32_bf16 v[54:57], v[154:157], v[192:195], v[78:81]
	v_mfma_f32_16x16x32_bf16 v[46:49], v[86:89], v[204:207], v[46:49]
	v_mfma_f32_16x16x32_bf16 v[34:37], v[188:191], v[204:207], v[34:37]
	v_mfma_f32_16x16x32_bf16 v[26:29], v[86:89], v[228:231], v[26:29]
	v_mfma_f32_16x16x32_bf16 v[18:21], v[188:191], v[228:231], v[18:21]
	v_mfma_f32_16x16x32_bf16 v[14:17], v[86:89], v[236:239], v[14:17]
	v_mfma_f32_16x16x32_bf16 v[2:5], v[188:191], v[236:239], v[2:5]
	v_mfma_f32_16x16x32_bf16 v[50:53], v[86:89], v[196:199], v[50:53]
	v_mfma_f32_16x16x32_bf16 v[54:57], v[188:191], v[196:199], v[54:57]
	s_barrier
	s_setprio 0
	s_add_i32 s68, 0, 0x18000
	s_add_i32 s69, 0, 0x1c000
	v_add_u32_e32 v78, s68, v220
	v_add_u32_e32 v82, s69, v220
	ds_read_b128 v[66:69], v78
	ds_read_b128 v[70:73], v78 offset:1024
	ds_read_b128 v[74:77], v78 offset:2048
	ds_read_b128 v[78:81], v78 offset:3072
	ds_read_b128 v[86:89], v82
	ds_read_b128 v[154:157], v82 offset:1024
	ds_read_b128 v[188:191], v82 offset:2048
	ds_read_b128 v[192:195], v82 offset:3072
	s_add_u32 s24, s24, 0x100000
	s_addc_u32 s25, s25, 0
	s_mov_b32 m0, s12
	v_lshl_add_u64 v[240:241], s[24:25], 0, v[176:177]
	ds_read_b128 v[82:85], v222 offset:32768
	ds_read_b128 v[196:199], v222 offset:33792
	ds_read_b128 v[200:203], v222 offset:34816
	ds_read_b128 v[204:207], v222 offset:35840
	ds_read_b128 v[224:227], v222 offset:36864
	ds_read_b128 v[228:231], v222 offset:37888
	ds_read_b128 v[232:235], v222 offset:38912
	ds_read_b128 v[236:239], v222 offset:39936
	global_load_lds_dwordx4 v[240:241], off
	v_lshl_add_u64 v[240:241], s[24:25], 0, v[174:175]
	s_mov_b32 m0, s13
	s_nop 0
	global_load_lds_dwordx4 v[240:241], off
	s_waitcnt vmcnt(8)
	s_waitcnt lgkmcnt(0)
	s_setprio 3
	s_barrier
	v_mfma_f32_16x16x32_bf16 v[142:145], v[66:69], v[82:85], v[142:145]
	v_mfma_f32_16x16x32_bf16 v[130:133], v[74:77], v[82:85], v[130:133]
	v_mfma_f32_16x16x32_bf16 v[138:141], v[66:69], v[200:203], v[138:141]
	v_mfma_f32_16x16x32_bf16 v[126:129], v[74:77], v[200:203], v[126:129]
	v_mfma_f32_16x16x32_bf16 v[118:121], v[66:69], v[224:227], v[118:121]
	v_mfma_f32_16x16x32_bf16 v[110:113], v[74:77], v[224:227], v[110:113]
	v_mfma_f32_16x16x32_bf16 v[98:101], v[66:69], v[232:235], v[98:101]
	v_mfma_f32_16x16x32_bf16 v[94:97], v[74:77], v[232:235], v[94:97]
	v_mfma_f32_16x16x32_bf16 v[142:145], v[70:73], v[196:199], v[142:145]
	v_mfma_f32_16x16x32_bf16 v[130:133], v[78:81], v[196:199], v[130:133]
	v_mfma_f32_16x16x32_bf16 v[138:141], v[70:73], v[204:207], v[138:141]
	v_mfma_f32_16x16x32_bf16 v[126:129], v[78:81], v[204:207], v[126:129]
	v_mfma_f32_16x16x32_bf16 v[118:121], v[70:73], v[228:231], v[118:121]
	v_mfma_f32_16x16x32_bf16 v[110:113], v[78:81], v[228:231], v[110:113]
	v_mfma_f32_16x16x32_bf16 v[98:101], v[70:73], v[236:239], v[98:101]
	v_mfma_f32_16x16x32_bf16 v[94:97], v[78:81], v[236:239], v[94:97]
	v_mfma_f32_16x16x32_bf16 v[150:153], v[86:89], v[82:85], v[150:153]
	v_mfma_f32_16x16x32_bf16 v[82:85], v[188:191], v[82:85], v[146:149]
	v_mfma_f32_16x16x32_bf16 v[146:149], v[192:195], v[196:199], v[82:85]
	v_mfma_f32_16x16x32_bf16 v[82:85], v[86:89], v[200:203], v[134:137]
	v_mfma_f32_16x16x32_bf16 v[134:137], v[154:157], v[204:207], v[82:85]
	v_mfma_f32_16x16x32_bf16 v[82:85], v[188:191], v[200:203], v[122:125]
	v_mfma_f32_16x16x32_bf16 v[122:125], v[192:195], v[204:207], v[82:85]
	v_mfma_f32_16x16x32_bf16 v[82:85], v[86:89], v[224:227], v[114:117]
	v_mfma_f32_16x16x32_bf16 v[114:117], v[154:157], v[228:231], v[82:85]
	v_mfma_f32_16x16x32_bf16 v[82:85], v[188:191], v[224:227], v[106:109]
	v_mfma_f32_16x16x32_bf16 v[106:109], v[192:195], v[228:231], v[82:85]
	v_mfma_f32_16x16x32_bf16 v[82:85], v[86:89], v[232:235], v[102:105]
	v_mfma_f32_16x16x32_bf16 v[102:105], v[154:157], v[236:239], v[82:85]
	v_mfma_f32_16x16x32_bf16 v[82:85], v[188:191], v[232:235], v[90:93]
	v_mfma_f32_16x16x32_bf16 v[150:153], v[154:157], v[196:199], v[150:153]
	v_mfma_f32_16x16x32_bf16 v[90:93], v[192:195], v[236:239], v[82:85]
	s_barrier
; #define PG8_STAGE(bufoff, gbase, voff) do { _Pragma("unroll") for (int _i = 0; _i < 2; ++_i) \
;         __builtin_amdgcn_global_load_lds((const unsigned*)((const char*)(gbase) + (voff)[_i]), (PG8_LAS unsigned*)(lds + (bufoff) + ldsw + _i * 8192), 16, 0, 0); } while (0)
; #define PG8_LDA(dst, b, h) do { _Pragma("unroll") for (int m = 0; m < 4; ++m) _Pragma("unroll") for (int k = 0; k < 2; ++k) dst[m][k] = *(const PG8_LAS bf16x8*)(lds + PG8_SA(b, h) + aoff + m * 2048 + k * 1024); } while (0)
; #define PG8_MMA(ai, bj, At, Bt) do { __builtin_amdgcn_s_setprio(1); _Pragma("unroll") for (int m = 0; m < 4; ++m) _Pragma("unroll") for (int n = 0; n < 2; ++n) _Pragma("unroll") for (int k = 0; k < 2; ++k) \
;         acc[ai][bj][m][n] = __builtin_amdgcn_mfma_f32_16x16x32_bf16(Bt[n][k], At[m][k], acc[ai][bj][m][n], 0, 0, 0); __builtin_amdgcn_s_setprio(0); } while (0)
; #define PG8_WAIT_V(n) asm volatile("s_waitcnt vmcnt(" #n ")" ::: "memory")
; #define PG8_WAIT_L(n) asm volatile("s_waitcnt lgkmcnt(" #n ")" ::: "memory")
; #define PG8_BAR __builtin_amdgcn_s_barrier()
; #define PG8_SCHED __builtin_amdgcn_sched_barrier(0)
; template <class Epi, class Sched, bool ALIGN_EPI = false, bool SP2 = false>
; __device__ __forceinline__ void gemm_phase(PG8_LAS unsigned char* lds, const Gemm g, const Sched& S, const Epi& E) {
;     ...
;             PG8_WAIT_V(8); PG8_WAIT_L(0); PG8_BAR; PG8_MMA(0, 0, At, B0); PG8_MMA(0, 1, At, B1); PG8_BAR; PG8_SCHED;
;             PG8_LDA(At, 1, 1); PG8_STAGE(PG8_SB(1, 0), b3, voffB); PG8_STAGE(PG8_SB(1, 1), b3 + hstep, voffB); PG8_STAGE(PG8_SA(1, 0), a3, voffA);
;             PG8_WAIT_V(8); PG8_WAIT_L(0); PG8_BAR; PG8_MMA(1, 0, At, B0); PG8_MMA(1, 1, At, B1); PG8_BAR; PG8_SCHED;
	s_setprio 0
	s_add_i32 s24, s68, s9
	s_nop 2
	v_lshl_add_u64 v[82:83], v[170:171], 0, s[96:97]
	s_mov_b32 m0, s24
	ds_read_b128 v[196:199], v222 offset:49152
	ds_read_b128 v[200:203], v222 offset:50176
	ds_read_b128 v[204:207], v222 offset:51200
	ds_read_b128 v[224:227], v222 offset:52224
	ds_read_b128 v[228:231], v222 offset:53248
	ds_read_b128 v[232:235], v222 offset:54272
	ds_read_b128 v[236:239], v222 offset:55296
	ds_read_b128 v[240:243], v222 offset:56320
	global_load_lds_dwordx4 v[82:83], off
	s_add_i32 m0, s24, 0x2000
	s_add_u32 s22, s22, 0x100080
	v_lshl_add_u64 v[82:83], v[208:209], 0, s[96:97]
	s_addc_u32 s23, s23, 0
	s_add_i32 s24, s69, s9
	global_load_lds_dwordx4 v[82:83], off
	v_lshl_add_u64 v[82:83], s[22:23], 0, v[158:159]
	s_mov_b32 m0, s24
	s_nop 0
	global_load_lds_dwordx4 v[82:83], off
	v_lshl_add_u64 v[82:83], s[22:23], 0, v[172:173]
	s_add_i32 m0, s24, 0x2000
	s_nop 0
	global_load_lds_dwordx4 v[82:83], off
	v_lshl_add_u64 v[82:83], v[210:211], 0, s[96:97]
	s_mov_b32 m0, s0
	s_nop 0
	global_load_lds_dwordx4 v[82:83], off
	v_lshl_add_u64 v[82:83], v[244:245], 0, s[96:97]
	s_mov_b32 m0, s34
	s_nop 0
	global_load_lds_dwordx4 v[82:83], off
	s_waitcnt vmcnt(8)
	s_waitcnt lgkmcnt(0)
	s_setprio 3
	s_barrier
	v_mfma_f32_16x16x32_bf16 v[62:65], v[66:69], v[196:199], v[62:65]
	v_mfma_f32_16x16x32_bf16 v[42:45], v[74:77], v[196:199], v[42:45]
	v_mfma_f32_16x16x32_bf16 v[58:61], v[66:69], v[204:207], v[58:61]
	v_mfma_f32_16x16x32_bf16 v[38:41], v[74:77], v[204:207], v[38:41]
	v_mfma_f32_16x16x32_bf16 v[30:33], v[66:69], v[228:231], v[30:33]
	v_mfma_f32_16x16x32_bf16 v[22:25], v[74:77], v[228:231], v[22:25]
	v_mfma_f32_16x16x32_bf16 v[10:13], v[66:69], v[236:239], v[10:13]
	v_mfma_f32_16x16x32_bf16 v[6:9], v[74:77], v[236:239], v[6:9]
	v_mfma_f32_16x16x32_bf16 v[62:65], v[70:73], v[200:203], v[62:65]
	v_mfma_f32_16x16x32_bf16 v[42:45], v[78:81], v[200:203], v[42:45]
	v_mfma_f32_16x16x32_bf16 v[58:61], v[70:73], v[224:227], v[58:61]
	v_mfma_f32_16x16x32_bf16 v[38:41], v[78:81], v[224:227], v[38:41]
	v_mfma_f32_16x16x32_bf16 v[30:33], v[70:73], v[232:235], v[30:33]
	v_mfma_f32_16x16x32_bf16 v[22:25], v[78:81], v[232:235], v[22:25]
	v_mfma_f32_16x16x32_bf16 v[10:13], v[70:73], v[240:243], v[10:13]
	v_mfma_f32_16x16x32_bf16 v[6:9], v[78:81], v[240:243], v[6:9]
	v_mfma_f32_16x16x32_bf16 v[50:53], v[86:89], v[196:199], v[50:53]
	v_mfma_f32_16x16x32_bf16 v[82:85], v[154:157], v[200:203], v[50:53]
	v_mfma_f32_16x16x32_bf16 v[50:53], v[188:191], v[196:199], v[54:57]
	v_mfma_f32_16x16x32_bf16 v[46:49], v[86:89], v[204:207], v[46:49]
	v_mfma_f32_16x16x32_bf16 v[34:37], v[188:191], v[204:207], v[34:37]
	v_mfma_f32_16x16x32_bf16 v[26:29], v[86:89], v[228:231], v[26:29]
	v_mfma_f32_16x16x32_bf16 v[18:21], v[188:191], v[228:231], v[18:21]
	v_mfma_f32_16x16x32_bf16 v[14:17], v[86:89], v[236:239], v[14:17]
	v_mfma_f32_16x16x32_bf16 v[2:5], v[188:191], v[236:239], v[2:5]
	v_mfma_f32_16x16x32_bf16 v[78:81], v[192:195], v[200:203], v[50:53]
	v_mfma_f32_16x16x32_bf16 v[46:49], v[154:157], v[224:227], v[46:49]
	v_mfma_f32_16x16x32_bf16 v[34:37], v[192:195], v[224:227], v[34:37]
	v_mfma_f32_16x16x32_bf16 v[26:29], v[154:157], v[232:235], v[26:29]
	v_mfma_f32_16x16x32_bf16 v[18:21], v[192:195], v[232:235], v[18:21]
	v_mfma_f32_16x16x32_bf16 v[14:17], v[154:157], v[240:243], v[14:17]
	v_mfma_f32_16x16x32_bf16 v[2:5], v[192:195], v[240:243], v[2:5]
	s_barrier
	s_setprio 0
	s_add_i32 s65, s65, 2
	s_add_u32 s16, s16, 0x100
	s_addc_u32 s17, s17, 0
	s_add_u32 vcc_lo, vcc_lo, 0x100
	s_addc_u32 vcc_hi, vcc_hi, 0
	s_cmp_gt_u32 s65, 61
	s_cbranch_scc0 .LBB0_710
	s_and_b64 vcc, exec, s[54:55]
	s_cbranch_vccz .LBB0_713
	s_barrier

; #define PG8_STAGE(bufoff, gbase, voff) do { _Pragma("unroll") for (int _i = 0; _i < 2; ++_i) \
;         __builtin_amdgcn_global_load_lds((const unsigned*)((const char*)(gbase) + (voff)[_i]), (PG8_LAS unsigned*)(lds + (bufoff) + ldsw + _i * 8192), 16, 0, 0); } while (0)
; #define PG8_LDA(dst, b, h) do { _Pragma("unroll") for (int m = 0; m < 4; ++m) _Pragma("unroll") for (int k = 0; k < 2; ++k) dst[m][k] = *(const PG8_LAS bf16x8*)(lds + PG8_SA(b, h) + aoff + m * 2048 + k * 1024); } while (0)
; #define PG8_LDB(dst, b, h) do { _Pragma("unroll") for (int n = 0; n < 2; ++n) _Pragma("unroll") for (int k = 0; k < 2; ++k) dst[n][k] = *(const PG8_LAS bf16x8*)(lds + PG8_SB(b, h) + boff + n * 2048 + k * 1024); } while (0)
; #define PG8_MMA(ai, bj, At, Bt) do { __builtin_amdgcn_s_setprio(1); _Pragma("unroll") for (int m = 0; m < 4; ++m) _Pragma("unroll") for (int n = 0; n < 2; ++n) _Pragma("unroll") for (int k = 0; k < 2; ++k) \
;         acc[ai][bj][m][n] = __builtin_amdgcn_mfma_f32_16x16x32_bf16(Bt[n][k], At[m][k], acc[ai][bj][m][n], 0, 0, 0); __builtin_amdgcn_s_setprio(0); } while (0)
; #define PG8_WAIT_V(n) asm volatile("s_waitcnt vmcnt(" #n ")" ::: "memory")
; #define PG8_BAR __builtin_amdgcn_s_barrier()
; template <class Epi, class Sched, bool ALIGN_EPI = false, bool SP2 = false>
; __device__ __forceinline__ void gemm_phase(PG8_LAS unsigned char* lds, const Gemm g, const Sched& S, const Epi& E) {
;     ...
;         for (int t = 0; t < nt; t += 2) {
;             const bool last = (t == nt - 2);
;             const char* a1 = cA + (size_t)(t + 1) * kstep;
;             const char* a2 = last ? nA : cA + (size_t)(t + 2) * kstep; const char* b2 = last ? nB : cB + (size_t)(t + 2) * kstep;
;             const char* a3 = a2 + kstep; const char* b3 = b2 + kstep;
;             if (last && has_next) S.a_ready(nxt);
;             if constexpr (SP2) {
;             PG8_LDB(B0, 0, 0); PG8_LDB(B1, 0, 1); PG8_SCHED; PG8_LDA(At, 0, 0); PG8_STAGE(PG8_SA(1, 1), a1 + hstep, voffA);
;             PG8_WAIT_V(8); PG8_WAIT_L(0); PG8_BAR; PG8_MMA(0, 0, At, B0); PG8_MMA(0, 1, At, B1); PG8_BAR; PG8_SCHED;
;             PG8_LDA(At, 0, 1); PG8_STAGE(PG8_SB(0, 0), b2, voffB); PG8_STAGE(PG8_SB(0, 1), b2 + hstep, voffB); PG8_STAGE(PG8_SA(0, 0), a2, voffA);
;             PG8_WAIT_V(8); PG8_WAIT_L(0); PG8_BAR; PG8_MMA(1, 0, At, B0); PG8_MMA(1, 1, At, B1); PG8_BAR; PG8_SCHED;
.LBB0_915:
	s_add_i32 s30, s28, 2
	s_add_u32 s26, s48, 0x100
	s_addc_u32 s27, s49, 0
	s_add_i32 s43, 0, 0x10000
	s_cmp_eq_u32 s15, s28
	s_cselect_b32 s51, s45, s27
	s_cselect_b32 s50, s44, s26
	s_cselect_b32 s29, s47, s17
	s_cselect_b32 s28, s46, s16
	s_add_i32 s59, 0, 0x14000
	v_add_u32_e32 v142, s43, v188
	v_add_u32_e32 v170, s59, v188
	ds_read_b128 v[130:133], v142
	ds_read_b128 v[134:137], v142 offset:1024
	ds_read_b128 v[138:141], v142 offset:2048
	ds_read_b128 v[142:145], v142 offset:3072
	ds_read_b128 v[146:149], v170
	ds_read_b128 v[150:153], v170 offset:1024
	ds_read_b128 v[178:181], v170 offset:2048
	ds_read_b128 v[182:185], v170 offset:3072
	v_lshl_add_u64 v[170:171], s[48:49], 0, v[176:177]
	s_add_i32 m0, s9, 0xc000
	ds_read_b128 v[192:195], v190
	ds_read_b128 v[196:199], v190 offset:1024
	ds_read_b128 v[200:203], v190 offset:2048
	ds_read_b128 v[204:207], v190 offset:3072
	ds_read_b128 v[220:223], v190 offset:4096
	ds_read_b128 v[224:227], v190 offset:5120
	ds_read_b128 v[228:231], v190 offset:6144
	ds_read_b128 v[232:235], v190 offset:7168
	global_load_lds_dwordx4 v[170:171], off
	v_lshl_add_u64 v[170:171], s[48:49], 0, v[174:175]
	s_add_i32 m0, s9, 0xe000
	s_nop 0
	global_load_lds_dwordx4 v[170:171], off
	s_waitcnt vmcnt(8)
	s_waitcnt lgkmcnt(0)
	s_setprio 3
	s_barrier
	v_mfma_f32_16x16x32_bf16 v[126:129], v[130:133], v[192:195], v[126:129]
	v_mfma_f32_16x16x32_bf16 v[122:125], v[138:141], v[192:195], v[122:125]
	v_mfma_f32_16x16x32_bf16 v[118:121], v[130:133], v[200:203], v[118:121]
	v_mfma_f32_16x16x32_bf16 v[114:117], v[138:141], v[200:203], v[114:117]
	v_mfma_f32_16x16x32_bf16 v[102:105], v[130:133], v[220:223], v[102:105]
	v_mfma_f32_16x16x32_bf16 v[94:97], v[138:141], v[220:223], v[94:97]
	v_mfma_f32_16x16x32_bf16 v[86:89], v[130:133], v[228:231], v[86:89]
	v_mfma_f32_16x16x32_bf16 v[78:81], v[138:141], v[228:231], v[78:81]
	v_mfma_f32_16x16x32_bf16 v[126:129], v[134:137], v[196:199], v[126:129]
	v_mfma_f32_16x16x32_bf16 v[122:125], v[142:145], v[196:199], v[122:125]
	v_mfma_f32_16x16x32_bf16 v[118:121], v[134:137], v[204:207], v[118:121]
	v_mfma_f32_16x16x32_bf16 v[114:117], v[142:145], v[204:207], v[114:117]
	v_mfma_f32_16x16x32_bf16 v[102:105], v[134:137], v[224:227], v[102:105]
	v_mfma_f32_16x16x32_bf16 v[94:97], v[142:145], v[224:227], v[94:97]
	v_mfma_f32_16x16x32_bf16 v[86:89], v[134:137], v[232:235], v[86:89]
	v_mfma_f32_16x16x32_bf16 v[78:81], v[142:145], v[232:235], v[78:81]
	v_mfma_f32_16x16x32_bf16 v[110:113], v[146:149], v[192:195], v[110:113]
	v_mfma_f32_16x16x32_bf16 v[106:109], v[178:181], v[192:195], v[106:109]
	v_mfma_f32_16x16x32_bf16 v[98:101], v[146:149], v[200:203], v[98:101]
	v_mfma_f32_16x16x32_bf16 v[90:93], v[178:181], v[200:203], v[90:93]
	v_mfma_f32_16x16x32_bf16 v[82:85], v[146:149], v[220:223], v[82:85]
	v_mfma_f32_16x16x32_bf16 v[74:77], v[178:181], v[220:223], v[74:77]
	v_mfma_f32_16x16x32_bf16 v[70:73], v[146:149], v[228:231], v[70:73]
	v_mfma_f32_16x16x32_bf16 v[66:69], v[178:181], v[228:231], v[66:69]
	v_mfma_f32_16x16x32_bf16 v[110:113], v[150:153], v[196:199], v[110:113]
	v_mfma_f32_16x16x32_bf16 v[106:109], v[182:185], v[196:199], v[106:109]
	v_mfma_f32_16x16x32_bf16 v[98:101], v[150:153], v[204:207], v[98:101]
	v_mfma_f32_16x16x32_bf16 v[90:93], v[182:185], v[204:207], v[90:93]
	v_mfma_f32_16x16x32_bf16 v[82:85], v[150:153], v[224:227], v[82:85]
	v_mfma_f32_16x16x32_bf16 v[74:77], v[182:185], v[224:227], v[74:77]
	v_mfma_f32_16x16x32_bf16 v[70:73], v[150:153], v[232:235], v[70:73]
	v_mfma_f32_16x16x32_bf16 v[66:69], v[182:185], v[232:235], v[66:69]
	s_barrier
	s_setprio 0
	s_add_i32 s43, s43, s8
	v_lshl_add_u64 v[170:171], s[28:29], 0, v[158:159]
	s_mov_b32 m0, s43
	ds_read_b128 v[192:195], v190 offset:16384
	ds_read_b128 v[196:199], v190 offset:17408
	ds_read_b128 v[200:203], v190 offset:18432
	ds_read_b128 v[204:207], v190 offset:19456
	ds_read_b128 v[220:223], v190 offset:20480
	ds_read_b128 v[224:227], v190 offset:21504
	ds_read_b128 v[228:231], v190 offset:22528
	ds_read_b128 v[232:235], v190 offset:23552
	global_load_lds_dwordx4 v[170:171], off
	s_add_i32 m0, s43, 0x2000
	s_add_u32 s48, s28, 0x2b0000
	v_lshl_add_u64 v[186:187], s[28:29], 0, v[172:173]
	s_addc_u32 s49, s29, 0
	s_add_i32 s43, s59, s8
	global_load_lds_dwordx4 v[186:187], off
	v_lshl_add_u64 v[208:209], s[48:49], 0, v[158:159]
	s_mov_b32 m0, s43
	v_lshl_add_u64 v[210:211], s[50:51], 0, v[156:157]
	global_load_lds_dwordx4 v[208:209], off
	v_lshl_add_u64 v[208:209], s[48:49], 0, v[172:173]
	s_add_i32 m0, s43, 0x2000
	s_nop 0
	global_load_lds_dwordx4 v[208:209], off
	v_lshl_add_u64 v[208:209], s[50:51], 0, v[154:155]
	s_mov_b32 m0, s9
	s_nop 0
	global_load_lds_dwordx4 v[208:209], off
	s_mov_b32 m0, s10
	s_nop 0
	global_load_lds_dwordx4 v[210:211], off
	s_waitcnt vmcnt(8)
	s_waitcnt lgkmcnt(0)
	s_setprio 3
	s_barrier
; #define PG8_STAGE(bufoff, gbase, voff) do { _Pragma("unroll") for (int _i = 0; _i < 2; ++_i) \
;         __builtin_amdgcn_global_load_lds((const unsigned*)((const char*)(gbase) + (voff)[_i]), (PG8_LAS unsigned*)(lds + (bufoff) + ldsw + _i * 8192), 16, 0, 0); } while (0)
; #define PG8_LDA(dst, b, h) do { _Pragma("unroll") for (int m = 0; m < 4; ++m) _Pragma("unroll") for (int k = 0; k < 2; ++k) dst[m][k] = *(const PG8_LAS bf16x8*)(lds + PG8_SA(b, h) + aoff + m * 2048 + k * 1024); } while (0)
; #define PG8_LDB(dst, b, h) do { _Pragma("unroll") for (int n = 0; n < 2; ++n) _Pragma("unroll") for (int k = 0; k < 2; ++k) dst[n][k] = *(const PG8_LAS bf16x8*)(lds + PG8_SB(b, h) + boff + n * 2048 + k * 1024); } while (0)
; #define PG8_MMA(ai, bj, At, Bt) do { __builtin_amdgcn_s_setprio(1); _Pragma("unroll") for (int m = 0; m < 4; ++m) _Pragma("unroll") for (int n = 0; n < 2; ++n) _Pragma("unroll") for (int k = 0; k < 2; ++k) \
;         acc[ai][bj][m][n] = __builtin_amdgcn_mfma_f32_16x16x32_bf16(Bt[n][k], At[m][k], acc[ai][bj][m][n], 0, 0, 0); __builtin_amdgcn_s_setprio(0); } while (0)
; #define PG8_WAIT_V(n) asm volatile("s_waitcnt vmcnt(" #n ")" ::: "memory")
; #define PG8_WAIT_L(n) asm volatile("s_waitcnt lgkmcnt(" #n ")" ::: "memory")
; #define PG8_BAR __builtin_amdgcn_s_barrier()
; #define PG8_SCHED __builtin_amdgcn_sched_barrier(0)
; template <class Epi, class Sched, bool ALIGN_EPI = false, bool SP2 = false>
; __device__ __forceinline__ void gemm_phase(PG8_LAS unsigned char* lds, const Gemm g, const Sched& S, const Epi& E) {
;     ...
;             PG8_WAIT_V(8); PG8_WAIT_L(0); PG8_BAR; PG8_MMA(1, 0, At, B0); PG8_MMA(1, 1, At, B1); PG8_BAR; PG8_SCHED;
;             PG8_LDB(B0, 1, 0); PG8_LDB(B1, 1, 1); PG8_SCHED; PG8_LDA(At, 1, 0); PG8_STAGE(PG8_SA(0, 1), a2 + hstep, voffA);
;             PG8_WAIT_V(8); PG8_WAIT_L(0); PG8_BAR; PG8_MMA(0, 0, At, B0); PG8_MMA(0, 1, At, B1); PG8_BAR; PG8_SCHED;
	v_mfma_f32_16x16x32_bf16 v[62:65], v[130:133], v[192:195], v[62:65]
	v_mfma_f32_16x16x32_bf16 v[58:61], v[138:141], v[192:195], v[58:61]
	v_mfma_f32_16x16x32_bf16 v[54:57], v[130:133], v[200:203], v[54:57]
	v_mfma_f32_16x16x32_bf16 v[46:49], v[138:141], v[200:203], v[46:49]
	v_mfma_f32_16x16x32_bf16 v[38:41], v[130:133], v[220:223], v[38:41]
	v_mfma_f32_16x16x32_bf16 v[30:33], v[138:141], v[220:223], v[30:33]
	v_mfma_f32_16x16x32_bf16 v[22:25], v[130:133], v[228:231], v[22:25]
	v_mfma_f32_16x16x32_bf16 v[14:17], v[138:141], v[228:231], v[14:17]
	v_mfma_f32_16x16x32_bf16 v[62:65], v[134:137], v[196:199], v[62:65]
	v_mfma_f32_16x16x32_bf16 v[58:61], v[142:145], v[196:199], v[58:61]
	v_mfma_f32_16x16x32_bf16 v[54:57], v[134:137], v[204:207], v[54:57]
	v_mfma_f32_16x16x32_bf16 v[46:49], v[142:145], v[204:207], v[46:49]
	v_mfma_f32_16x16x32_bf16 v[38:41], v[134:137], v[224:227], v[38:41]
	v_mfma_f32_16x16x32_bf16 v[30:33], v[142:145], v[224:227], v[30:33]
	v_mfma_f32_16x16x32_bf16 v[22:25], v[134:137], v[232:235], v[22:25]
	v_mfma_f32_16x16x32_bf16 v[14:17], v[142:145], v[232:235], v[14:17]
	v_mfma_f32_16x16x32_bf16 v[50:53], v[146:149], v[192:195], v[50:53]
	v_mfma_f32_16x16x32_bf16 v[42:45], v[178:181], v[192:195], v[42:45]
	v_mfma_f32_16x16x32_bf16 v[34:37], v[146:149], v[200:203], v[34:37]
	v_mfma_f32_16x16x32_bf16 v[26:29], v[178:181], v[200:203], v[26:29]
	v_mfma_f32_16x16x32_bf16 v[18:21], v[146:149], v[220:223], v[18:21]
	v_mfma_f32_16x16x32_bf16 v[10:13], v[178:181], v[220:223], v[10:13]
	v_mfma_f32_16x16x32_bf16 v[6:9], v[146:149], v[228:231], v[6:9]
	v_mfma_f32_16x16x32_bf16 v[2:5], v[178:181], v[228:231], v[2:5]
	v_mfma_f32_16x16x32_bf16 v[50:53], v[150:153], v[196:199], v[50:53]
	v_mfma_f32_16x16x32_bf16 v[42:45], v[182:185], v[196:199], v[42:45]
	v_mfma_f32_16x16x32_bf16 v[34:37], v[150:153], v[204:207], v[34:37]
	v_mfma_f32_16x16x32_bf16 v[26:29], v[182:185], v[204:207], v[26:29]
	v_mfma_f32_16x16x32_bf16 v[18:21], v[150:153], v[224:227], v[18:21]
	v_mfma_f32_16x16x32_bf16 v[10:13], v[182:185], v[224:227], v[10:13]
	v_mfma_f32_16x16x32_bf16 v[6:9], v[150:153], v[232:235], v[6:9]
	v_mfma_f32_16x16x32_bf16 v[2:5], v[182:185], v[232:235], v[2:5]
	s_barrier
	s_setprio 0
	s_add_i32 s43, 0, 0x18000
	s_add_i32 s59, 0, 0x1c000
	v_add_u32_e32 v142, s43, v188
	v_add_u32_e32 v182, s59, v188
	ds_read_b128 v[130:133], v142
	ds_read_b128 v[134:137], v142 offset:1024
	ds_read_b128 v[138:141], v142 offset:2048
	ds_read_b128 v[142:145], v142 offset:3072
	ds_read_b128 v[146:149], v182
	ds_read_b128 v[150:153], v182 offset:1024
	ds_read_b128 v[178:181], v182 offset:2048
	ds_read_b128 v[182:185], v182 offset:3072
	s_add_u32 s48, s50, 0x2b0000
	s_addc_u32 s49, s51, 0
	s_mov_b32 m0, s11
	v_lshl_add_u64 v[236:237], s[48:49], 0, v[154:155]
	ds_read_b128 v[192:195], v190 offset:32768
	ds_read_b128 v[196:199], v190 offset:33792
	ds_read_b128 v[200:203], v190 offset:34816
	ds_read_b128 v[204:207], v190 offset:35840
	ds_read_b128 v[220:223], v190 offset:36864
	ds_read_b128 v[224:227], v190 offset:37888
	ds_read_b128 v[228:231], v190 offset:38912
	ds_read_b128 v[232:235], v190 offset:39936
	global_load_lds_dwordx4 v[236:237], off
	v_lshl_add_u64 v[236:237], s[48:49], 0, v[156:157]
	s_mov_b32 m0, s12
	s_nop 0
	global_load_lds_dwordx4 v[236:237], off
	s_waitcnt vmcnt(8)
	s_waitcnt lgkmcnt(0)
	s_setprio 3
	s_barrier
	v_mfma_f32_16x16x32_bf16 v[126:129], v[130:133], v[192:195], v[126:129]
	v_mfma_f32_16x16x32_bf16 v[122:125], v[138:141], v[192:195], v[122:125]
	v_mfma_f32_16x16x32_bf16 v[118:121], v[130:133], v[200:203], v[118:121]
	v_mfma_f32_16x16x32_bf16 v[114:117], v[138:141], v[200:203], v[114:117]
	v_mfma_f32_16x16x32_bf16 v[102:105], v[130:133], v[220:223], v[102:105]
	v_mfma_f32_16x16x32_bf16 v[94:97], v[138:141], v[220:223], v[94:97]
	v_mfma_f32_16x16x32_bf16 v[86:89], v[130:133], v[228:231], v[86:89]
	v_mfma_f32_16x16x32_bf16 v[78:81], v[138:141], v[228:231], v[78:81]
	v_mfma_f32_16x16x32_bf16 v[126:129], v[134:137], v[196:199], v[126:129]
	v_mfma_f32_16x16x32_bf16 v[122:125], v[142:145], v[196:199], v[122:125]
	v_mfma_f32_16x16x32_bf16 v[118:121], v[134:137], v[204:207], v[118:121]
	v_mfma_f32_16x16x32_bf16 v[114:117], v[142:145], v[204:207], v[114:117]
	v_mfma_f32_16x16x32_bf16 v[102:105], v[134:137], v[224:227], v[102:105]
	v_mfma_f32_16x16x32_bf16 v[94:97], v[142:145], v[224:227], v[94:97]
	v_mfma_f32_16x16x32_bf16 v[86:89], v[134:137], v[232:235], v[86:89]
	v_mfma_f32_16x16x32_bf16 v[78:81], v[142:145], v[232:235], v[78:81]
	v_mfma_f32_16x16x32_bf16 v[110:113], v[146:149], v[192:195], v[110:113]
	v_mfma_f32_16x16x32_bf16 v[106:109], v[178:181], v[192:195], v[106:109]
	v_mfma_f32_16x16x32_bf16 v[98:101], v[146:149], v[200:203], v[98:101]
	v_mfma_f32_16x16x32_bf16 v[90:93], v[178:181], v[200:203], v[90:93]
	v_mfma_f32_16x16x32_bf16 v[82:85], v[146:149], v[220:223], v[82:85]
	v_mfma_f32_16x16x32_bf16 v[74:77], v[178:181], v[220:223], v[74:77]
	v_mfma_f32_16x16x32_bf16 v[70:73], v[146:149], v[228:231], v[70:73]
	v_mfma_f32_16x16x32_bf16 v[66:69], v[178:181], v[228:231], v[66:69]
	v_mfma_f32_16x16x32_bf16 v[110:113], v[150:153], v[196:199], v[110:113]
	v_mfma_f32_16x16x32_bf16 v[106:109], v[182:185], v[196:199], v[106:109]
	v_mfma_f32_16x16x32_bf16 v[98:101], v[150:153], v[204:207], v[98:101]
	v_mfma_f32_16x16x32_bf16 v[90:93], v[182:185], v[204:207], v[90:93]
	v_mfma_f32_16x16x32_bf16 v[82:85], v[150:153], v[224:227], v[82:85]
	v_mfma_f32_16x16x32_bf16 v[74:77], v[182:185], v[224:227], v[74:77]
	v_mfma_f32_16x16x32_bf16 v[70:73], v[150:153], v[232:235], v[70:73]
	v_mfma_f32_16x16x32_bf16 v[66:69], v[182:185], v[232:235], v[66:69]
	s_barrier
; #define PG8_STAGE(bufoff, gbase, voff) do { _Pragma("unroll") for (int _i = 0; _i < 2; ++_i) \
;         __builtin_amdgcn_global_load_lds((const unsigned*)((const char*)(gbase) + (voff)[_i]), (PG8_LAS unsigned*)(lds + (bufoff) + ldsw + _i * 8192), 16, 0, 0); } while (0)
; #define PG8_LDA(dst, b, h) do { _Pragma("unroll") for (int m = 0; m < 4; ++m) _Pragma("unroll") for (int k = 0; k < 2; ++k) dst[m][k] = *(const PG8_LAS bf16x8*)(lds + PG8_SA(b, h) + aoff + m * 2048 + k * 1024); } while (0)
; #define PG8_MMA(ai, bj, At, Bt) do { __builtin_amdgcn_s_setprio(1); _Pragma("unroll") for (int m = 0; m < 4; ++m) _Pragma("unroll") for (int n = 0; n < 2; ++n) _Pragma("unroll") for (int k = 0; k < 2; ++k) \
;         acc[ai][bj][m][n] = __builtin_amdgcn_mfma_f32_16x16x32_bf16(Bt[n][k], At[m][k], acc[ai][bj][m][n], 0, 0, 0); __builtin_amdgcn_s_setprio(0); } while (0)
; #define PG8_WAIT_V(n) asm volatile("s_waitcnt vmcnt(" #n ")" ::: "memory")
; #define PG8_WAIT_L(n) asm volatile("s_waitcnt lgkmcnt(" #n ")" ::: "memory")
; #define PG8_BAR __builtin_amdgcn_s_barrier()
; #define PG8_SCHED __builtin_amdgcn_sched_barrier(0)
; template <class Epi, class Sched, bool ALIGN_EPI = false, bool SP2 = false>
; __device__ __forceinline__ void gemm_phase(PG8_LAS unsigned char* lds, const Gemm g, const Sched& S, const Epi& E) {
;     ...
;             PG8_WAIT_V(8); PG8_WAIT_L(0); PG8_BAR; PG8_MMA(0, 0, At, B0); PG8_MMA(0, 1, At, B1); PG8_BAR; PG8_SCHED;
;             PG8_LDA(At, 1, 1); PG8_STAGE(PG8_SB(1, 0), b3, voffB); PG8_STAGE(PG8_SB(1, 1), b3 + hstep, voffB); PG8_STAGE(PG8_SA(1, 0), a3, voffA);
;             PG8_WAIT_V(8); PG8_WAIT_L(0); PG8_BAR; PG8_MMA(1, 0, At, B0); PG8_MMA(1, 1, At, B1); PG8_BAR; PG8_SCHED;
	s_setprio 0
	s_add_i32 s43, s43, s8
	v_lshl_add_u64 v[170:171], v[170:171], 0, s[96:97]
	s_mov_b32 m0, s43
	ds_read_b128 v[192:195], v190 offset:49152
	ds_read_b128 v[196:199], v190 offset:50176
	ds_read_b128 v[200:203], v190 offset:51200
	ds_read_b128 v[204:207], v190 offset:52224
	ds_read_b128 v[220:223], v190 offset:53248
	ds_read_b128 v[224:227], v190 offset:54272
	ds_read_b128 v[228:231], v190 offset:55296
	ds_read_b128 v[232:235], v190 offset:56320
	global_load_lds_dwordx4 v[170:171], off
	s_add_i32 m0, s43, 0x2000
	s_add_u32 s28, s28, 0x2b0080
	v_lshl_add_u64 v[170:171], v[186:187], 0, s[96:97]
	s_addc_u32 s29, s29, 0
	s_add_i32 s43, s59, s8
	global_load_lds_dwordx4 v[170:171], off
	v_lshl_add_u64 v[170:171], s[28:29], 0, v[158:159]
	s_mov_b32 m0, s43
	s_nop 0
	global_load_lds_dwordx4 v[170:171], off
	v_lshl_add_u64 v[170:171], s[28:29], 0, v[172:173]
	s_add_i32 m0, s43, 0x2000
	s_nop 0
	global_load_lds_dwordx4 v[170:171], off
	v_lshl_add_u64 v[170:171], v[208:209], 0, s[96:97]
	s_mov_b32 m0, s35
	s_nop 0
	global_load_lds_dwordx4 v[170:171], off
	v_lshl_add_u64 v[170:171], v[210:211], 0, s[96:97]
	s_mov_b32 m0, s52
	s_nop 0
	global_load_lds_dwordx4 v[170:171], off
	s_waitcnt vmcnt(8)
	s_waitcnt lgkmcnt(0)
	s_setprio 3
	s_barrier
	v_mfma_f32_16x16x32_bf16 v[62:65], v[130:133], v[192:195], v[62:65]
	v_mfma_f32_16x16x32_bf16 v[58:61], v[138:141], v[192:195], v[58:61]
	v_mfma_f32_16x16x32_bf16 v[54:57], v[130:133], v[200:203], v[54:57]
	v_mfma_f32_16x16x32_bf16 v[46:49], v[138:141], v[200:203], v[46:49]
	v_mfma_f32_16x16x32_bf16 v[38:41], v[130:133], v[220:223], v[38:41]
	v_mfma_f32_16x16x32_bf16 v[30:33], v[138:141], v[220:223], v[30:33]
	v_mfma_f32_16x16x32_bf16 v[22:25], v[130:133], v[228:231], v[22:25]
	v_mfma_f32_16x16x32_bf16 v[14:17], v[138:141], v[228:231], v[14:17]
	v_mfma_f32_16x16x32_bf16 v[62:65], v[134:137], v[196:199], v[62:65]
	v_mfma_f32_16x16x32_bf16 v[58:61], v[142:145], v[196:199], v[58:61]
	v_mfma_f32_16x16x32_bf16 v[54:57], v[134:137], v[204:207], v[54:57]
	v_mfma_f32_16x16x32_bf16 v[46:49], v[142:145], v[204:207], v[46:49]
	v_mfma_f32_16x16x32_bf16 v[38:41], v[134:137], v[224:227], v[38:41]
	v_mfma_f32_16x16x32_bf16 v[30:33], v[142:145], v[224:227], v[30:33]
	v_mfma_f32_16x16x32_bf16 v[22:25], v[134:137], v[232:235], v[22:25]
	v_mfma_f32_16x16x32_bf16 v[14:17], v[142:145], v[232:235], v[14:17]
	v_mfma_f32_16x16x32_bf16 v[50:53], v[146:149], v[192:195], v[50:53]
	v_mfma_f32_16x16x32_bf16 v[42:45], v[178:181], v[192:195], v[42:45]
	v_mfma_f32_16x16x32_bf16 v[34:37], v[146:149], v[200:203], v[34:37]
	v_mfma_f32_16x16x32_bf16 v[26:29], v[178:181], v[200:203], v[26:29]
	v_mfma_f32_16x16x32_bf16 v[18:21], v[146:149], v[220:223], v[18:21]
	v_mfma_f32_16x16x32_bf16 v[10:13], v[178:181], v[220:223], v[10:13]
	v_mfma_f32_16x16x32_bf16 v[6:9], v[146:149], v[228:231], v[6:9]
	v_mfma_f32_16x16x32_bf16 v[2:5], v[178:181], v[228:231], v[2:5]
	v_mfma_f32_16x16x32_bf16 v[50:53], v[150:153], v[196:199], v[50:53]
	v_mfma_f32_16x16x32_bf16 v[42:45], v[182:185], v[196:199], v[42:45]
	v_mfma_f32_16x16x32_bf16 v[34:37], v[150:153], v[204:207], v[34:37]
	v_mfma_f32_16x16x32_bf16 v[26:29], v[182:185], v[204:207], v[26:29]
	v_mfma_f32_16x16x32_bf16 v[18:21], v[150:153], v[224:227], v[18:21]
	v_mfma_f32_16x16x32_bf16 v[10:13], v[182:185], v[224:227], v[10:13]
	v_mfma_f32_16x16x32_bf16 v[6:9], v[150:153], v[232:235], v[6:9]
	v_mfma_f32_16x16x32_bf16 v[2:5], v[182:185], v[232:235], v[2:5]
	s_barrier
	s_setprio 0
	s_add_u32 s16, s16, 0x100
	s_addc_u32 s17, s17, 0
	s_cmp_ge_i32 s30, s14
	s_mov_b64 s[48:49], s[26:27]
	s_mov_b32 s28, s30
	s_cbranch_scc0 .LBB0_915
	s_and_b64 vcc, exec, s[40:41]
	s_cbranch_vccz .LBB0_918
	s_barrier
